# HGRN second pass (fix) rewritten by hand: staging loads batched, row tiles software-pipelined with counted vmcnt, global instead of flat loads
# speedup vs baseline: 1.0230x; 1.0200x over previous
.LBB0_672:
	s_or_b64 exec, exec, s[0:1]
	s_mov_b64 s[6:7], s[46:47]
	s_waitcnt lgkmcnt(0)
	s_barrier
	v_lshlrev_b32_e32 v0, 7, v194
	v_lshrrev_b32_e32 v1, 2, v194
	v_and_b32_e32 v2, 3, v194
	v_mul_u32_u24_e32 v2, 0x2200, v2
	v_lshl_add_u32 v2, v1, 1, v2
	v_lshlrev_b32_e32 v1, 2, v1
	s_mul_i32 s0, s2, 6
	s_lshr_b32 s12, s0, 3
	s_add_i32 s0, s0, 5
	s_lshr_b32 s13, s0, 3
	s_and_b32 s40, s12, 3
	s_and_b32 s41, s13, 3
	s_cmp_eq_u32 s12, s13
	s_cselect_b32 s41, 0, s41
	s_cmp_eq_u32 s40, 0
	s_cbranch_scc1 .Lfix_iss_done0
	s_lshr_b32 s0, s12, 2
	s_lshl_b32 s1, s0, 18
	s_add_u32 s4, s46, s1
	s_addc_u32 s5, s47, 0
	s_add_u32 s4, s4, 0x4200000
	s_addc_u32 s5, s5, 0
	global_load_dwordx4 v[4:7], v0, s[4:5]
	global_load_dwordx4 v[8:11], v0, s[4:5] offset:16
	global_load_dwordx4 v[12:15], v0, s[4:5] offset:32
	global_load_dwordx4 v[16:19], v0, s[4:5] offset:48
	global_load_dwordx4 v[20:23], v0, s[4:5] offset:64
	global_load_dwordx4 v[24:27], v0, s[4:5] offset:80
	global_load_dwordx4 v[28:31], v0, s[4:5] offset:96
	global_load_dwordx4 v[32:35], v0, s[4:5] offset:112
	s_cmp_lt_u32 s40, 2
	s_cbranch_scc1 .Lfix_iss_done0
	s_add_u32 s4, s4, 0x10000
	s_addc_u32 s5, s5, 0
	global_load_dwordx4 v[36:39], v0, s[4:5]
	global_load_dwordx4 v[40:43], v0, s[4:5] offset:16
	global_load_dwordx4 v[44:47], v0, s[4:5] offset:32
	global_load_dwordx4 v[48:51], v0, s[4:5] offset:48
	global_load_dwordx4 v[52:55], v0, s[4:5] offset:64
	global_load_dwordx4 v[56:59], v0, s[4:5] offset:80
	global_load_dwordx4 v[60:63], v0, s[4:5] offset:96
	global_load_dwordx4 v[64:67], v0, s[4:5] offset:112
	s_lshl_b32 s1, s0, 11
	s_add_u32 s6, s46, s1
	s_addc_u32 s7, s47, 0
	s_add_u32 s6, s6, 0x5200200
	s_addc_u32 s7, s7, 0
	global_load_dword v100, v1, s[6:7]
	s_cmp_lt_u32 s40, 3
	s_cbranch_scc1 .Lfix_iss_done0
	s_add_u32 s4, s4, 0x10000
	s_addc_u32 s5, s5, 0
	global_load_dwordx4 v[68:71], v0, s[4:5]
	global_load_dwordx4 v[72:75], v0, s[4:5] offset:16
	global_load_dwordx4 v[76:79], v0, s[4:5] offset:32
	global_load_dwordx4 v[80:83], v0, s[4:5] offset:48
	global_load_dwordx4 v[84:87], v0, s[4:5] offset:64
	global_load_dwordx4 v[88:91], v0, s[4:5] offset:80
	global_load_dwordx4 v[92:95], v0, s[4:5] offset:96
	global_load_dwordx4 v[96:99], v0, s[4:5] offset:112
	global_load_dword v102, v1, s[6:7] offset:512
.Lfix_iss_done0:
	s_cmp_eq_u32 s41, 0
	s_cbranch_scc1 .Lfix_iss_done1
	s_lshr_b32 s0, s13, 2
	s_lshl_b32 s1, s0, 18
	s_add_u32 s4, s46, s1
	s_addc_u32 s5, s47, 0
	s_add_u32 s4, s4, 0x4200000
	s_addc_u32 s5, s5, 0
	global_load_dwordx4 v[104:107], v0, s[4:5]
	global_load_dwordx4 v[108:111], v0, s[4:5] offset:16
	global_load_dwordx4 v[112:115], v0, s[4:5] offset:32
	global_load_dwordx4 v[116:119], v0, s[4:5] offset:48
	global_load_dwordx4 v[120:123], v0, s[4:5] offset:64
	global_load_dwordx4 v[124:127], v0, s[4:5] offset:80
	global_load_dwordx4 v[128:131], v0, s[4:5] offset:96
	global_load_dwordx4 v[132:135], v0, s[4:5] offset:112
	s_cmp_lt_u32 s41, 2
	s_cbranch_scc1 .Lfix_iss_done1
	s_add_u32 s4, s4, 0x10000
	s_addc_u32 s5, s5, 0
	global_load_dwordx4 v[136:139], v0, s[4:5]
	global_load_dwordx4 v[140:143], v0, s[4:5] offset:16
	global_load_dwordx4 v[144:147], v0, s[4:5] offset:32
	global_load_dwordx4 v[148:151], v0, s[4:5] offset:48
	global_load_dwordx4 v[152:155], v0, s[4:5] offset:64
	global_load_dwordx4 v[172:175], v0, s[4:5] offset:80
	global_load_dwordx4 v[176:179], v0, s[4:5] offset:96
	global_load_dwordx4 v[180:183], v0, s[4:5] offset:112
	s_lshl_b32 s1, s0, 11
	s_add_u32 s6, s46, s1
	s_addc_u32 s7, s47, 0
	s_add_u32 s6, s6, 0x5200200
	s_addc_u32 s7, s7, 0
	global_load_dword v224, v1, s[6:7]
	s_cmp_lt_u32 s41, 3
	s_cbranch_scc1 .Lfix_iss_done1
	s_add_u32 s4, s4, 0x10000
	s_addc_u32 s5, s5, 0
	global_load_dwordx4 v[184:187], v0, s[4:5]
	global_load_dwordx4 v[188:191], v0, s[4:5] offset:16
	global_load_dwordx4 v[200:203], v0, s[4:5] offset:32
	global_load_dwordx4 v[204:207], v0, s[4:5] offset:48
	global_load_dwordx4 v[208:211], v0, s[4:5] offset:64
	global_load_dwordx4 v[212:215], v0, s[4:5] offset:80
	global_load_dwordx4 v[216:219], v0, s[4:5] offset:96
	global_load_dwordx4 v[220:223], v0, s[4:5] offset:112
	global_load_dword v226, v1, s[6:7] offset:512
.Lfix_iss_done1:
	s_waitcnt vmcnt(0)
	s_cmp_eq_u32 s40, 0
	s_cbranch_scc1 .Lfix_proc_done0
	s_cmp_lt_u32 s40, 2
	s_cbranch_scc1 .Lfix_cvt0
	v_pk_fma_f32 v[4:5], v[4:5], v[100:101], v[36:37] op_sel_hi:[1,0,1]
	v_pk_fma_f32 v[6:7], v[6:7], v[100:101], v[38:39] op_sel_hi:[1,0,1]
	v_pk_fma_f32 v[8:9], v[8:9], v[100:101], v[40:41] op_sel_hi:[1,0,1]
	v_pk_fma_f32 v[10:11], v[10:11], v[100:101], v[42:43] op_sel_hi:[1,0,1]
	v_pk_fma_f32 v[12:13], v[12:13], v[100:101], v[44:45] op_sel_hi:[1,0,1]
	v_pk_fma_f32 v[14:15], v[14:15], v[100:101], v[46:47] op_sel_hi:[1,0,1]
	v_pk_fma_f32 v[16:17], v[16:17], v[100:101], v[48:49] op_sel_hi:[1,0,1]
	v_pk_fma_f32 v[18:19], v[18:19], v[100:101], v[50:51] op_sel_hi:[1,0,1]
	v_pk_fma_f32 v[20:21], v[20:21], v[100:101], v[52:53] op_sel_hi:[1,0,1]
	v_pk_fma_f32 v[22:23], v[22:23], v[100:101], v[54:55] op_sel_hi:[1,0,1]
	v_pk_fma_f32 v[24:25], v[24:25], v[100:101], v[56:57] op_sel_hi:[1,0,1]
	v_pk_fma_f32 v[26:27], v[26:27], v[100:101], v[58:59] op_sel_hi:[1,0,1]
	v_pk_fma_f32 v[28:29], v[28:29], v[100:101], v[60:61] op_sel_hi:[1,0,1]
	v_pk_fma_f32 v[30:31], v[30:31], v[100:101], v[62:63] op_sel_hi:[1,0,1]
	v_pk_fma_f32 v[32:33], v[32:33], v[100:101], v[64:65] op_sel_hi:[1,0,1]
	v_pk_fma_f32 v[34:35], v[34:35], v[100:101], v[66:67] op_sel_hi:[1,0,1]
	s_cmp_lt_u32 s40, 3
	s_cbranch_scc1 .Lfix_cvt0
	v_pk_fma_f32 v[4:5], v[4:5], v[102:103], v[68:69] op_sel_hi:[1,0,1]
	v_pk_fma_f32 v[6:7], v[6:7], v[102:103], v[70:71] op_sel_hi:[1,0,1]
	v_pk_fma_f32 v[8:9], v[8:9], v[102:103], v[72:73] op_sel_hi:[1,0,1]
	v_pk_fma_f32 v[10:11], v[10:11], v[102:103], v[74:75] op_sel_hi:[1,0,1]
	v_pk_fma_f32 v[12:13], v[12:13], v[102:103], v[76:77] op_sel_hi:[1,0,1]
	v_pk_fma_f32 v[14:15], v[14:15], v[102:103], v[78:79] op_sel_hi:[1,0,1]
	v_pk_fma_f32 v[16:17], v[16:17], v[102:103], v[80:81] op_sel_hi:[1,0,1]
	v_pk_fma_f32 v[18:19], v[18:19], v[102:103], v[82:83] op_sel_hi:[1,0,1]
	v_pk_fma_f32 v[20:21], v[20:21], v[102:103], v[84:85] op_sel_hi:[1,0,1]
	v_pk_fma_f32 v[22:23], v[22:23], v[102:103], v[86:87] op_sel_hi:[1,0,1]
	v_pk_fma_f32 v[24:25], v[24:25], v[102:103], v[88:89] op_sel_hi:[1,0,1]
	v_pk_fma_f32 v[26:27], v[26:27], v[102:103], v[90:91] op_sel_hi:[1,0,1]
	v_pk_fma_f32 v[28:29], v[28:29], v[102:103], v[92:93] op_sel_hi:[1,0,1]
	v_pk_fma_f32 v[30:31], v[30:31], v[102:103], v[94:95] op_sel_hi:[1,0,1]
	v_pk_fma_f32 v[32:33], v[32:33], v[102:103], v[96:97] op_sel_hi:[1,0,1]
	v_pk_fma_f32 v[34:35], v[34:35], v[102:103], v[98:99] op_sel_hi:[1,0,1]
.Lfix_cvt0:
	v_cvt_pk_bf16_f32 v228, v4, v5
	ds_write_b16 v2, v228 offset:0
	ds_write_b16_d16_hi v2, v228 offset:272
	v_cvt_pk_bf16_f32 v229, v6, v7
	ds_write_b16 v2, v229 offset:544
	ds_write_b16_d16_hi v2, v229 offset:816
	v_cvt_pk_bf16_f32 v230, v8, v9
	ds_write_b16 v2, v230 offset:1088
	ds_write_b16_d16_hi v2, v230 offset:1360
	v_cvt_pk_bf16_f32 v231, v10, v11
	ds_write_b16 v2, v231 offset:1632
	ds_write_b16_d16_hi v2, v231 offset:1904
	v_cvt_pk_bf16_f32 v228, v12, v13
	ds_write_b16 v2, v228 offset:2176
	ds_write_b16_d16_hi v2, v228 offset:2448
	v_cvt_pk_bf16_f32 v229, v14, v15
	ds_write_b16 v2, v229 offset:2720
	ds_write_b16_d16_hi v2, v229 offset:2992
	v_cvt_pk_bf16_f32 v230, v16, v17
	ds_write_b16 v2, v230 offset:3264
	ds_write_b16_d16_hi v2, v230 offset:3536
	v_cvt_pk_bf16_f32 v231, v18, v19
	ds_write_b16 v2, v231 offset:3808
	ds_write_b16_d16_hi v2, v231 offset:4080
	v_cvt_pk_bf16_f32 v228, v20, v21
	ds_write_b16 v2, v228 offset:4352
	ds_write_b16_d16_hi v2, v228 offset:4624
	v_cvt_pk_bf16_f32 v229, v22, v23
	ds_write_b16 v2, v229 offset:4896
	ds_write_b16_d16_hi v2, v229 offset:5168
	v_cvt_pk_bf16_f32 v230, v24, v25
	ds_write_b16 v2, v230 offset:5440
	ds_write_b16_d16_hi v2, v230 offset:5712
	v_cvt_pk_bf16_f32 v231, v26, v27
	ds_write_b16 v2, v231 offset:5984
	ds_write_b16_d16_hi v2, v231 offset:6256
	v_cvt_pk_bf16_f32 v228, v28, v29
	ds_write_b16 v2, v228 offset:6528
	ds_write_b16_d16_hi v2, v228 offset:6800
	v_cvt_pk_bf16_f32 v229, v30, v31
	ds_write_b16 v2, v229 offset:7072
	ds_write_b16_d16_hi v2, v229 offset:7344
	v_cvt_pk_bf16_f32 v230, v32, v33
	ds_write_b16 v2, v230 offset:7616
	ds_write_b16_d16_hi v2, v230 offset:7888
	v_cvt_pk_bf16_f32 v231, v34, v35
	ds_write_b16 v2, v231 offset:8160
	ds_write_b16_d16_hi v2, v231 offset:8432
.Lfix_proc_done0:
	s_cmp_eq_u32 s41, 0
	s_cbranch_scc1 .Lfix_proc_done1
	s_cmp_lt_u32 s41, 2
	s_cbranch_scc1 .Lfix_cvt1
	v_pk_fma_f32 v[104:105], v[104:105], v[224:225], v[136:137] op_sel_hi:[1,0,1]
	v_pk_fma_f32 v[106:107], v[106:107], v[224:225], v[138:139] op_sel_hi:[1,0,1]
	v_pk_fma_f32 v[108:109], v[108:109], v[224:225], v[140:141] op_sel_hi:[1,0,1]
	v_pk_fma_f32 v[110:111], v[110:111], v[224:225], v[142:143] op_sel_hi:[1,0,1]
	v_pk_fma_f32 v[112:113], v[112:113], v[224:225], v[144:145] op_sel_hi:[1,0,1]
	v_pk_fma_f32 v[114:115], v[114:115], v[224:225], v[146:147] op_sel_hi:[1,0,1]
	v_pk_fma_f32 v[116:117], v[116:117], v[224:225], v[148:149] op_sel_hi:[1,0,1]
	v_pk_fma_f32 v[118:119], v[118:119], v[224:225], v[150:151] op_sel_hi:[1,0,1]
	v_pk_fma_f32 v[120:121], v[120:121], v[224:225], v[152:153] op_sel_hi:[1,0,1]
	v_pk_fma_f32 v[122:123], v[122:123], v[224:225], v[154:155] op_sel_hi:[1,0,1]
	v_pk_fma_f32 v[124:125], v[124:125], v[224:225], v[172:173] op_sel_hi:[1,0,1]
	v_pk_fma_f32 v[126:127], v[126:127], v[224:225], v[174:175] op_sel_hi:[1,0,1]
	v_pk_fma_f32 v[128:129], v[128:129], v[224:225], v[176:177] op_sel_hi:[1,0,1]
	v_pk_fma_f32 v[130:131], v[130:131], v[224:225], v[178:179] op_sel_hi:[1,0,1]
	v_pk_fma_f32 v[132:133], v[132:133], v[224:225], v[180:181] op_sel_hi:[1,0,1]
	v_pk_fma_f32 v[134:135], v[134:135], v[224:225], v[182:183] op_sel_hi:[1,0,1]
	s_cmp_lt_u32 s41, 3
	s_cbranch_scc1 .Lfix_cvt1
	v_pk_fma_f32 v[104:105], v[104:105], v[226:227], v[184:185] op_sel_hi:[1,0,1]
	v_pk_fma_f32 v[106:107], v[106:107], v[226:227], v[186:187] op_sel_hi:[1,0,1]
	v_pk_fma_f32 v[108:109], v[108:109], v[226:227], v[188:189] op_sel_hi:[1,0,1]
	v_pk_fma_f32 v[110:111], v[110:111], v[226:227], v[190:191] op_sel_hi:[1,0,1]
	v_pk_fma_f32 v[112:113], v[112:113], v[226:227], v[200:201] op_sel_hi:[1,0,1]
	v_pk_fma_f32 v[114:115], v[114:115], v[226:227], v[202:203] op_sel_hi:[1,0,1]
	v_pk_fma_f32 v[116:117], v[116:117], v[226:227], v[204:205] op_sel_hi:[1,0,1]
	v_pk_fma_f32 v[118:119], v[118:119], v[226:227], v[206:207] op_sel_hi:[1,0,1]
	v_pk_fma_f32 v[120:121], v[120:121], v[226:227], v[208:209] op_sel_hi:[1,0,1]
	v_pk_fma_f32 v[122:123], v[122:123], v[226:227], v[210:211] op_sel_hi:[1,0,1]
	v_pk_fma_f32 v[124:125], v[124:125], v[226:227], v[212:213] op_sel_hi:[1,0,1]
	v_pk_fma_f32 v[126:127], v[126:127], v[226:227], v[214:215] op_sel_hi:[1,0,1]
	v_pk_fma_f32 v[128:129], v[128:129], v[226:227], v[216:217] op_sel_hi:[1,0,1]
	v_pk_fma_f32 v[130:131], v[130:131], v[226:227], v[218:219] op_sel_hi:[1,0,1]
	v_pk_fma_f32 v[132:133], v[132:133], v[226:227], v[220:221] op_sel_hi:[1,0,1]
	v_pk_fma_f32 v[134:135], v[134:135], v[226:227], v[222:223] op_sel_hi:[1,0,1]
.Lfix_cvt1:
	v_cvt_pk_bf16_f32 v228, v104, v105
	ds_write_b16 v2, v228 offset:34816
	ds_write_b16_d16_hi v2, v228 offset:35088
	v_cvt_pk_bf16_f32 v229, v106, v107
	ds_write_b16 v2, v229 offset:35360
	ds_write_b16_d16_hi v2, v229 offset:35632
	v_cvt_pk_bf16_f32 v230, v108, v109
	ds_write_b16 v2, v230 offset:35904
	ds_write_b16_d16_hi v2, v230 offset:36176
	v_cvt_pk_bf16_f32 v231, v110, v111
	ds_write_b16 v2, v231 offset:36448
	ds_write_b16_d16_hi v2, v231 offset:36720
	v_cvt_pk_bf16_f32 v228, v112, v113
	ds_write_b16 v2, v228 offset:36992
	ds_write_b16_d16_hi v2, v228 offset:37264
	v_cvt_pk_bf16_f32 v229, v114, v115
	ds_write_b16 v2, v229 offset:37536
	ds_write_b16_d16_hi v2, v229 offset:37808
	v_cvt_pk_bf16_f32 v230, v116, v117
	ds_write_b16 v2, v230 offset:38080
	ds_write_b16_d16_hi v2, v230 offset:38352
	v_cvt_pk_bf16_f32 v231, v118, v119
	ds_write_b16 v2, v231 offset:38624
	ds_write_b16_d16_hi v2, v231 offset:38896
	v_cvt_pk_bf16_f32 v228, v120, v121
	ds_write_b16 v2, v228 offset:39168
	ds_write_b16_d16_hi v2, v228 offset:39440
	v_cvt_pk_bf16_f32 v229, v122, v123
	ds_write_b16 v2, v229 offset:39712
	ds_write_b16_d16_hi v2, v229 offset:39984
	v_cvt_pk_bf16_f32 v230, v124, v125
	ds_write_b16 v2, v230 offset:40256
	ds_write_b16_d16_hi v2, v230 offset:40528
	v_cvt_pk_bf16_f32 v231, v126, v127
	ds_write_b16 v2, v231 offset:40800
	ds_write_b16_d16_hi v2, v231 offset:41072
	v_cvt_pk_bf16_f32 v228, v128, v129
	ds_write_b16 v2, v228 offset:41344
	ds_write_b16_d16_hi v2, v228 offset:41616
	v_cvt_pk_bf16_f32 v229, v130, v131
	ds_write_b16 v2, v229 offset:41888
	ds_write_b16_d16_hi v2, v229 offset:42160
	v_cvt_pk_bf16_f32 v230, v132, v133
	ds_write_b16 v2, v230 offset:42432
	ds_write_b16_d16_hi v2, v230 offset:42704
	v_cvt_pk_bf16_f32 v231, v134, v135
	ds_write_b16 v2, v231 offset:42976
	ds_write_b16_d16_hi v2, v231 offset:43248
.Lfix_proc_done1:
	s_waitcnt lgkmcnt(0)
	s_barrier
	v_readfirstlane_b32 s0, v194
	s_nop 3
	s_lshr_b32 s0, s0, 6
	s_cmp_gt_u32 s0, 5
	s_cbranch_scc1 .Lfix_end
	s_mul_i32 s1, s2, 6
	s_add_i32 s1, s1, s0
	s_and_b32 s13, s1, 7
	s_lshr_b32 s1, s1, 3
	s_cmp_lg_u32 s1, s12
	s_cselect_b32 s100, 0x8800, 0
	s_and_b32 s40, s1, 3
	s_lshr_b32 s1, s1, 2
	s_mul_i32 s101, s1, 43
	s_lshr_b32 s101, s101, 8
	s_mul_i32 s41, s101, 6
	s_sub_u32 s1, s1, s41
	s_lshl_b32 s41, s101, 12
	s_lshl_b32 s101, s40, 10
	s_add_u32 s41, s41, s101
	s_lshl_b32 s101, s13, 7
	s_add_u32 s41, s41, s101
	s_lshl_b32 s1, s1, 8
	s_mul_i32 s101, s41, 0x600
	s_add_u32 s101, s101, s1
	s_add_u32 s4, s44, s101
	s_addc_u32 s5, s45, 0
	s_add_u32 s6, s46, s101
	s_addc_u32 s7, s47, 0
	s_add_u32 s6, s6, 0x13200000
	s_addc_u32 s7, s7, 0
	s_lshl_b32 s101, s41, 11
	s_add_u32 s101, s101, s1
	s_add_u32 s8, s46, s101
	s_addc_u32 s9, s47, 0
	s_add_u32 s8, s8, 0x8200000
	s_addc_u32 s9, s9, 0
	s_mov_b64 s[10:11], s[8:9]
	v_and_b32_e32 v220, 15, v197
	v_lshrrev_b32_e32 v221, 4, v197
	v_mul_u32_u24_e32 v0, 0x600, v220
	v_lshl_add_u32 v1, v221, 3, v0
	v_lshl_add_u32 v0, v221, 4, v0
	v_lshlrev_b32_e32 v2, 11, v220
	v_lshl_add_u32 v2, v221, 3, v2
	v_mul_u32_u24_e32 v232, 0x110, v220
	v_lshl_add_u32 v232, v221, 4, v232
	v_add_u32_e32 v232, s100, v232
	v_xor_b32_e32 v233, 16, v197
	v_xor_b32_e32 v234, 32, v197
	v_lshlrev_b32_e32 v233, 2, v233
	v_lshlrev_b32_e32 v234, 2, v234
	global_load_dwordx4 v[36:39], v0, s[4:5]
	global_load_dwordx4 v[40:43], v0, s[4:5] offset:64
	global_load_dwordx4 v[44:47], v0, s[4:5] offset:128
	global_load_dwordx4 v[48:51], v0, s[4:5] offset:192
	global_load_dwordx2 v[52:53], v2, s[8:9]
	global_load_dwordx2 v[54:55], v2, s[8:9] offset:32
	global_load_dwordx2 v[56:57], v2, s[8:9] offset:64
	global_load_dwordx2 v[58:59], v2, s[8:9] offset:96
	global_load_dwordx2 v[60:61], v2, s[8:9] offset:128
	global_load_dwordx2 v[62:63], v2, s[8:9] offset:160
	global_load_dwordx2 v[64:65], v2, s[8:9] offset:192
	global_load_dwordx2 v[66:67], v2, s[8:9] offset:224
	global_load_dwordx2 v[68:69], v1, s[6:7]
	global_load_dwordx2 v[70:71], v1, s[6:7] offset:32
	global_load_dwordx2 v[72:73], v1, s[6:7] offset:64
	global_load_dwordx2 v[74:75], v1, s[6:7] offset:96
	global_load_dwordx2 v[76:77], v1, s[6:7] offset:128
	global_load_dwordx2 v[78:79], v1, s[6:7] offset:160
	global_load_dwordx2 v[80:81], v1, s[6:7] offset:192
	global_load_dwordx2 v[82:83], v1, s[6:7] offset:224
	s_add_u32 s4, s4, 0x6000
	s_addc_u32 s5, s5, 0
	s_add_u32 s6, s6, 0x6000
	s_addc_u32 s7, s7, 0
	s_add_u32 s8, s8, 0x8000
	s_addc_u32 s9, s9, 0
	global_load_dwordx4 v[84:87], v0, s[4:5]
	global_load_dwordx4 v[88:91], v0, s[4:5] offset:64
	global_load_dwordx4 v[92:95], v0, s[4:5] offset:128
	global_load_dwordx4 v[96:99], v0, s[4:5] offset:192
	global_load_dwordx2 v[100:101], v2, s[8:9]
	global_load_dwordx2 v[102:103], v2, s[8:9] offset:32
	global_load_dwordx2 v[104:105], v2, s[8:9] offset:64
	global_load_dwordx2 v[106:107], v2, s[8:9] offset:96
	global_load_dwordx2 v[108:109], v2, s[8:9] offset:128
	global_load_dwordx2 v[110:111], v2, s[8:9] offset:160
	global_load_dwordx2 v[112:113], v2, s[8:9] offset:192
	global_load_dwordx2 v[114:115], v2, s[8:9] offset:224
	global_load_dwordx2 v[116:117], v1, s[6:7]
	global_load_dwordx2 v[118:119], v1, s[6:7] offset:32
	global_load_dwordx2 v[120:121], v1, s[6:7] offset:64
	global_load_dwordx2 v[122:123], v1, s[6:7] offset:96
	global_load_dwordx2 v[124:125], v1, s[6:7] offset:128
	global_load_dwordx2 v[126:127], v1, s[6:7] offset:160
	global_load_dwordx2 v[128:129], v1, s[6:7] offset:192
	global_load_dwordx2 v[130:131], v1, s[6:7] offset:224
	s_add_u32 s4, s4, 0x6000
	s_addc_u32 s5, s5, 0
	s_add_u32 s6, s6, 0x6000
	s_addc_u32 s7, s7, 0
	s_add_u32 s8, s8, 0x8000
	s_addc_u32 s9, s9, 0
	s_cmp_eq_u32 s40, 0
	s_cbranch_scc1 .Lfix_nomm_t0
	s_waitcnt vmcnt(36)
	ds_read_b128 v[132:135], v232 offset:0
	ds_read_b128 v[136:139], v232 offset:64
	ds_read_b128 v[140:143], v232 offset:128
	ds_read_b128 v[144:147], v232 offset:192
	ds_read_b128 v[148:151], v232 offset:4352
	ds_read_b128 v[152:155], v232 offset:4416
	ds_read_b128 v[172:175], v232 offset:4480
	ds_read_b128 v[176:179], v232 offset:4544
	ds_read_b128 v[180:183], v232 offset:8704
	ds_read_b128 v[184:187], v232 offset:8768
	ds_read_b128 v[188:191], v232 offset:8832
	ds_read_b128 v[200:203], v232 offset:8896
	s_waitcnt lgkmcnt(8)
	v_mfma_f32_16x16x32_bf16 v[4:7], v[132:135], v[36:39], 0
	v_mfma_f32_16x16x32_bf16 v[4:7], v[136:139], v[40:43], v[4:7]
	v_mfma_f32_16x16x32_bf16 v[4:7], v[140:143], v[44:47], v[4:7]
	v_mfma_f32_16x16x32_bf16 v[4:7], v[144:147], v[48:51], v[4:7]
	ds_read_b128 v[132:135], v232 offset:13056
	ds_read_b128 v[136:139], v232 offset:13120
	ds_read_b128 v[140:143], v232 offset:13184
	ds_read_b128 v[144:147], v232 offset:13248
	s_waitcnt lgkmcnt(8)
	v_mfma_f32_16x16x32_bf16 v[8:11], v[148:151], v[36:39], 0
	v_mfma_f32_16x16x32_bf16 v[8:11], v[152:155], v[40:43], v[8:11]
	v_mfma_f32_16x16x32_bf16 v[8:11], v[172:175], v[44:47], v[8:11]
	v_mfma_f32_16x16x32_bf16 v[8:11], v[176:179], v[48:51], v[8:11]
	ds_read_b128 v[148:151], v232 offset:17408
	ds_read_b128 v[152:155], v232 offset:17472
	ds_read_b128 v[172:175], v232 offset:17536
	ds_read_b128 v[176:179], v232 offset:17600
	s_waitcnt lgkmcnt(8)
	v_mfma_f32_16x16x32_bf16 v[12:15], v[180:183], v[36:39], 0
	v_mfma_f32_16x16x32_bf16 v[12:15], v[184:187], v[40:43], v[12:15]
	v_mfma_f32_16x16x32_bf16 v[12:15], v[188:191], v[44:47], v[12:15]
	v_mfma_f32_16x16x32_bf16 v[12:15], v[200:203], v[48:51], v[12:15]
	ds_read_b128 v[180:183], v232 offset:21760
	ds_read_b128 v[184:187], v232 offset:21824
	ds_read_b128 v[188:191], v232 offset:21888
	ds_read_b128 v[200:203], v232 offset:21952
	s_waitcnt lgkmcnt(8)
	v_mfma_f32_16x16x32_bf16 v[16:19], v[132:135], v[36:39], 0
	v_mfma_f32_16x16x32_bf16 v[16:19], v[136:139], v[40:43], v[16:19]
	v_mfma_f32_16x16x32_bf16 v[16:19], v[140:143], v[44:47], v[16:19]
	v_mfma_f32_16x16x32_bf16 v[16:19], v[144:147], v[48:51], v[16:19]
	ds_read_b128 v[132:135], v232 offset:26112
	ds_read_b128 v[136:139], v232 offset:26176
	ds_read_b128 v[140:143], v232 offset:26240
	ds_read_b128 v[144:147], v232 offset:26304
	s_waitcnt lgkmcnt(8)
	v_mfma_f32_16x16x32_bf16 v[20:23], v[148:151], v[36:39], 0
	v_mfma_f32_16x16x32_bf16 v[20:23], v[152:155], v[40:43], v[20:23]
	v_mfma_f32_16x16x32_bf16 v[20:23], v[172:175], v[44:47], v[20:23]
	v_mfma_f32_16x16x32_bf16 v[20:23], v[176:179], v[48:51], v[20:23]
	ds_read_b128 v[148:151], v232 offset:30464
	ds_read_b128 v[152:155], v232 offset:30528
	ds_read_b128 v[172:175], v232 offset:30592
	ds_read_b128 v[176:179], v232 offset:30656
	s_waitcnt lgkmcnt(8)
	v_mfma_f32_16x16x32_bf16 v[24:27], v[180:183], v[36:39], 0
	v_mfma_f32_16x16x32_bf16 v[24:27], v[184:187], v[40:43], v[24:27]
	v_mfma_f32_16x16x32_bf16 v[24:27], v[188:191], v[44:47], v[24:27]
	v_mfma_f32_16x16x32_bf16 v[24:27], v[200:203], v[48:51], v[24:27]
	s_waitcnt lgkmcnt(4)
	v_mfma_f32_16x16x32_bf16 v[28:31], v[132:135], v[36:39], 0
	v_mfma_f32_16x16x32_bf16 v[28:31], v[136:139], v[40:43], v[28:31]
	v_mfma_f32_16x16x32_bf16 v[28:31], v[140:143], v[44:47], v[28:31]
	v_mfma_f32_16x16x32_bf16 v[28:31], v[144:147], v[48:51], v[28:31]
	s_waitcnt lgkmcnt(0)
	v_mfma_f32_16x16x32_bf16 v[32:35], v[148:151], v[36:39], 0
	v_mfma_f32_16x16x32_bf16 v[32:35], v[152:155], v[40:43], v[32:35]
	v_mfma_f32_16x16x32_bf16 v[32:35], v[172:175], v[44:47], v[32:35]
	v_mfma_f32_16x16x32_bf16 v[32:35], v[176:179], v[48:51], v[32:35]
	s_branch .Lfix_mmdone_t0
.Lfix_nomm_t0:
	v_mov_b32_e32 v4, 0
	v_mov_b32_e32 v5, 0
	v_mov_b32_e32 v6, 0
	v_mov_b32_e32 v7, 0
	v_mov_b32_e32 v8, 0
	v_mov_b32_e32 v9, 0
	v_mov_b32_e32 v10, 0
	v_mov_b32_e32 v11, 0
	v_mov_b32_e32 v12, 0
	v_mov_b32_e32 v13, 0
	v_mov_b32_e32 v14, 0
	v_mov_b32_e32 v15, 0
	v_mov_b32_e32 v16, 0
	v_mov_b32_e32 v17, 0
	v_mov_b32_e32 v18, 0
	v_mov_b32_e32 v19, 0
	v_mov_b32_e32 v20, 0
	v_mov_b32_e32 v21, 0
	v_mov_b32_e32 v22, 0
	v_mov_b32_e32 v23, 0
	v_mov_b32_e32 v24, 0
	v_mov_b32_e32 v25, 0
	v_mov_b32_e32 v26, 0
	v_mov_b32_e32 v27, 0
	v_mov_b32_e32 v28, 0
	v_mov_b32_e32 v29, 0
	v_mov_b32_e32 v30, 0
	v_mov_b32_e32 v31, 0
	v_mov_b32_e32 v32, 0
	v_mov_b32_e32 v33, 0
	v_mov_b32_e32 v34, 0
	v_mov_b32_e32 v35, 0
.Lfix_mmdone_t0:
	s_waitcnt vmcnt(28)
	v_lshlrev_b32_e32 v220, 16, v52
	v_and_b32_e32 v221, 0xffff0000, v52
	v_lshlrev_b32_e32 v222, 16, v53
	v_and_b32_e32 v223, 0xffff0000, v53
	v_pk_add_f32 v[4:5], v[4:5], v[220:221]
	v_pk_add_f32 v[6:7], v[6:7], v[222:223]
	v_pk_mul_f32 v[224:225], v[4:5], v[4:5]
	v_pk_fma_f32 v[224:225], v[6:7], v[6:7], v[224:225]
	v_lshlrev_b32_e32 v220, 16, v54
	v_and_b32_e32 v221, 0xffff0000, v54
	v_lshlrev_b32_e32 v222, 16, v55
	v_and_b32_e32 v223, 0xffff0000, v55
	v_pk_add_f32 v[8:9], v[8:9], v[220:221]
	v_pk_add_f32 v[10:11], v[10:11], v[222:223]
	v_pk_fma_f32 v[224:225], v[8:9], v[8:9], v[224:225]
	v_pk_fma_f32 v[224:225], v[10:11], v[10:11], v[224:225]
	v_lshlrev_b32_e32 v220, 16, v56
	v_and_b32_e32 v221, 0xffff0000, v56
	v_lshlrev_b32_e32 v222, 16, v57
	v_and_b32_e32 v223, 0xffff0000, v57
	v_pk_add_f32 v[12:13], v[12:13], v[220:221]
	v_pk_add_f32 v[14:15], v[14:15], v[222:223]
	v_pk_fma_f32 v[224:225], v[12:13], v[12:13], v[224:225]
	v_pk_fma_f32 v[224:225], v[14:15], v[14:15], v[224:225]
	v_lshlrev_b32_e32 v220, 16, v58
	v_and_b32_e32 v221, 0xffff0000, v58
	v_lshlrev_b32_e32 v222, 16, v59
	v_and_b32_e32 v223, 0xffff0000, v59
	v_pk_add_f32 v[16:17], v[16:17], v[220:221]
	v_pk_add_f32 v[18:19], v[18:19], v[222:223]
	v_pk_fma_f32 v[224:225], v[16:17], v[16:17], v[224:225]
	v_pk_fma_f32 v[224:225], v[18:19], v[18:19], v[224:225]
	v_lshlrev_b32_e32 v220, 16, v60
	v_and_b32_e32 v221, 0xffff0000, v60
	v_lshlrev_b32_e32 v222, 16, v61
	v_and_b32_e32 v223, 0xffff0000, v61
	v_pk_add_f32 v[20:21], v[20:21], v[220:221]
	v_pk_add_f32 v[22:23], v[22:23], v[222:223]
	v_pk_fma_f32 v[224:225], v[20:21], v[20:21], v[224:225]
	v_pk_fma_f32 v[224:225], v[22:23], v[22:23], v[224:225]
	v_lshlrev_b32_e32 v220, 16, v62
	v_and_b32_e32 v221, 0xffff0000, v62
	v_lshlrev_b32_e32 v222, 16, v63
	v_and_b32_e32 v223, 0xffff0000, v63
	v_pk_add_f32 v[24:25], v[24:25], v[220:221]
	v_pk_add_f32 v[26:27], v[26:27], v[222:223]
	v_pk_fma_f32 v[224:225], v[24:25], v[24:25], v[224:225]
	v_pk_fma_f32 v[224:225], v[26:27], v[26:27], v[224:225]
	v_lshlrev_b32_e32 v220, 16, v64
	v_and_b32_e32 v221, 0xffff0000, v64
	v_lshlrev_b32_e32 v222, 16, v65
	v_and_b32_e32 v223, 0xffff0000, v65
	v_pk_add_f32 v[28:29], v[28:29], v[220:221]
	v_pk_add_f32 v[30:31], v[30:31], v[222:223]
	v_pk_fma_f32 v[224:225], v[28:29], v[28:29], v[224:225]
	v_pk_fma_f32 v[224:225], v[30:31], v[30:31], v[224:225]
	v_lshlrev_b32_e32 v220, 16, v66
	v_and_b32_e32 v221, 0xffff0000, v66
	v_lshlrev_b32_e32 v222, 16, v67
	v_and_b32_e32 v223, 0xffff0000, v67
	v_pk_add_f32 v[32:33], v[32:33], v[220:221]
	v_pk_add_f32 v[34:35], v[34:35], v[222:223]
	v_pk_fma_f32 v[224:225], v[32:33], v[32:33], v[224:225]
	v_pk_fma_f32 v[224:225], v[34:35], v[34:35], v[224:225]
	v_add_f32_e32 v226, v224, v225
	ds_bpermute_b32 v227, v233, v226
	s_waitcnt lgkmcnt(0)
	v_add_f32_e32 v226, v226, v227
	ds_bpermute_b32 v227, v234, v226
	s_waitcnt lgkmcnt(0)
	v_add_f32_e32 v226, v226, v227
	v_fmamk_f32 v226, v226, 0x3c000000, v195
	v_rsq_f32_e32 v228, v226
	s_nop 0
	s_waitcnt vmcnt(20)
	v_pk_mul_f32 v[4:5], v[4:5], v[228:229] op_sel_hi:[1,0]
	v_pk_mul_f32 v[6:7], v[6:7], v[228:229] op_sel_hi:[1,0]
	v_lshlrev_b32_e32 v220, 16, v68
	v_and_b32_e32 v221, 0xffff0000, v68
	v_lshlrev_b32_e32 v222, 16, v69
	v_and_b32_e32 v223, 0xffff0000, v69
	v_pk_mul_f32 v[4:5], v[4:5], v[220:221]
	v_pk_mul_f32 v[6:7], v[6:7], v[222:223]
	v_cvt_pk_bf16_f32 v68, v4, v5
	v_cvt_pk_bf16_f32 v69, v6, v7
	global_store_dwordx2 v2, v[68:69], s[10:11]
	v_pk_mul_f32 v[8:9], v[8:9], v[228:229] op_sel_hi:[1,0]
	v_pk_mul_f32 v[10:11], v[10:11], v[228:229] op_sel_hi:[1,0]
	v_lshlrev_b32_e32 v220, 16, v70
	v_and_b32_e32 v221, 0xffff0000, v70
	v_lshlrev_b32_e32 v222, 16, v71
	v_and_b32_e32 v223, 0xffff0000, v71
	v_pk_mul_f32 v[8:9], v[8:9], v[220:221]
	v_pk_mul_f32 v[10:11], v[10:11], v[222:223]
	v_cvt_pk_bf16_f32 v70, v8, v9
	v_cvt_pk_bf16_f32 v71, v10, v11
	global_store_dwordx2 v2, v[70:71], s[10:11] offset:32
	v_pk_mul_f32 v[12:13], v[12:13], v[228:229] op_sel_hi:[1,0]
	v_pk_mul_f32 v[14:15], v[14:15], v[228:229] op_sel_hi:[1,0]
	v_lshlrev_b32_e32 v220, 16, v72
	v_and_b32_e32 v221, 0xffff0000, v72
	v_lshlrev_b32_e32 v222, 16, v73
	v_and_b32_e32 v223, 0xffff0000, v73
	v_pk_mul_f32 v[12:13], v[12:13], v[220:221]
	v_pk_mul_f32 v[14:15], v[14:15], v[222:223]
	v_cvt_pk_bf16_f32 v72, v12, v13
	v_cvt_pk_bf16_f32 v73, v14, v15
	global_store_dwordx2 v2, v[72:73], s[10:11] offset:64
	v_pk_mul_f32 v[16:17], v[16:17], v[228:229] op_sel_hi:[1,0]
	v_pk_mul_f32 v[18:19], v[18:19], v[228:229] op_sel_hi:[1,0]
	v_lshlrev_b32_e32 v220, 16, v74
	v_and_b32_e32 v221, 0xffff0000, v74
	v_lshlrev_b32_e32 v222, 16, v75
	v_and_b32_e32 v223, 0xffff0000, v75
	v_pk_mul_f32 v[16:17], v[16:17], v[220:221]
	v_pk_mul_f32 v[18:19], v[18:19], v[222:223]
	v_cvt_pk_bf16_f32 v74, v16, v17
	v_cvt_pk_bf16_f32 v75, v18, v19
	global_store_dwordx2 v2, v[74:75], s[10:11] offset:96
	v_pk_mul_f32 v[20:21], v[20:21], v[228:229] op_sel_hi:[1,0]
	v_pk_mul_f32 v[22:23], v[22:23], v[228:229] op_sel_hi:[1,0]
	v_lshlrev_b32_e32 v220, 16, v76
	v_and_b32_e32 v221, 0xffff0000, v76
	v_lshlrev_b32_e32 v222, 16, v77
	v_and_b32_e32 v223, 0xffff0000, v77
	v_pk_mul_f32 v[20:21], v[20:21], v[220:221]
	v_pk_mul_f32 v[22:23], v[22:23], v[222:223]
	v_cvt_pk_bf16_f32 v76, v20, v21
	v_cvt_pk_bf16_f32 v77, v22, v23
	global_store_dwordx2 v2, v[76:77], s[10:11] offset:128
	v_pk_mul_f32 v[24:25], v[24:25], v[228:229] op_sel_hi:[1,0]
	v_pk_mul_f32 v[26:27], v[26:27], v[228:229] op_sel_hi:[1,0]
	v_lshlrev_b32_e32 v220, 16, v78
	v_and_b32_e32 v221, 0xffff0000, v78
	v_lshlrev_b32_e32 v222, 16, v79
	v_and_b32_e32 v223, 0xffff0000, v79
	v_pk_mul_f32 v[24:25], v[24:25], v[220:221]
	v_pk_mul_f32 v[26:27], v[26:27], v[222:223]
	v_cvt_pk_bf16_f32 v78, v24, v25
	v_cvt_pk_bf16_f32 v79, v26, v27
	global_store_dwordx2 v2, v[78:79], s[10:11] offset:160
	v_pk_mul_f32 v[28:29], v[28:29], v[228:229] op_sel_hi:[1,0]
	v_pk_mul_f32 v[30:31], v[30:31], v[228:229] op_sel_hi:[1,0]
	v_lshlrev_b32_e32 v220, 16, v80
	v_and_b32_e32 v221, 0xffff0000, v80
	v_lshlrev_b32_e32 v222, 16, v81
	v_and_b32_e32 v223, 0xffff0000, v81
	v_pk_mul_f32 v[28:29], v[28:29], v[220:221]
	v_pk_mul_f32 v[30:31], v[30:31], v[222:223]
	v_cvt_pk_bf16_f32 v80, v28, v29
	v_cvt_pk_bf16_f32 v81, v30, v31
	global_store_dwordx2 v2, v[80:81], s[10:11] offset:192
	v_pk_mul_f32 v[32:33], v[32:33], v[228:229] op_sel_hi:[1,0]
	v_pk_mul_f32 v[34:35], v[34:35], v[228:229] op_sel_hi:[1,0]
	v_lshlrev_b32_e32 v220, 16, v82
	v_and_b32_e32 v221, 0xffff0000, v82
	v_lshlrev_b32_e32 v222, 16, v83
	v_and_b32_e32 v223, 0xffff0000, v83
	v_pk_mul_f32 v[32:33], v[32:33], v[220:221]
	v_pk_mul_f32 v[34:35], v[34:35], v[222:223]
	v_cvt_pk_bf16_f32 v82, v32, v33
	v_cvt_pk_bf16_f32 v83, v34, v35
	global_store_dwordx2 v2, v[82:83], s[10:11] offset:224
	s_add_u32 s10, s10, 0x8000
	s_addc_u32 s11, s11, 0
	s_mov_b32 s13, 3
.Lfix_loop:
	global_load_dwordx4 v[36:39], v0, s[4:5]
	global_load_dwordx4 v[40:43], v0, s[4:5] offset:64
	global_load_dwordx4 v[44:47], v0, s[4:5] offset:128
	global_load_dwordx4 v[48:51], v0, s[4:5] offset:192
	global_load_dwordx2 v[52:53], v2, s[8:9]
	global_load_dwordx2 v[54:55], v2, s[8:9] offset:32
	global_load_dwordx2 v[56:57], v2, s[8:9] offset:64
	global_load_dwordx2 v[58:59], v2, s[8:9] offset:96
	global_load_dwordx2 v[60:61], v2, s[8:9] offset:128
	global_load_dwordx2 v[62:63], v2, s[8:9] offset:160
	global_load_dwordx2 v[64:65], v2, s[8:9] offset:192
	global_load_dwordx2 v[66:67], v2, s[8:9] offset:224
	global_load_dwordx2 v[68:69], v1, s[6:7]
	global_load_dwordx2 v[70:71], v1, s[6:7] offset:32
	global_load_dwordx2 v[72:73], v1, s[6:7] offset:64
	global_load_dwordx2 v[74:75], v1, s[6:7] offset:96
	global_load_dwordx2 v[76:77], v1, s[6:7] offset:128
	global_load_dwordx2 v[78:79], v1, s[6:7] offset:160
	global_load_dwordx2 v[80:81], v1, s[6:7] offset:192
	global_load_dwordx2 v[82:83], v1, s[6:7] offset:224
	s_add_u32 s4, s4, 0x6000
	s_addc_u32 s5, s5, 0
	s_add_u32 s6, s6, 0x6000
	s_addc_u32 s7, s7, 0
	s_add_u32 s8, s8, 0x8000
	s_addc_u32 s9, s9, 0
	s_cmp_eq_u32 s40, 0
	s_cbranch_scc1 .Lfix_nomm_ta
	s_waitcnt vmcnt(44)
	ds_read_b128 v[132:135], v232 offset:0
	ds_read_b128 v[136:139], v232 offset:64
	ds_read_b128 v[140:143], v232 offset:128
	ds_read_b128 v[144:147], v232 offset:192
	ds_read_b128 v[148:151], v232 offset:4352
	ds_read_b128 v[152:155], v232 offset:4416
	ds_read_b128 v[172:175], v232 offset:4480
	ds_read_b128 v[176:179], v232 offset:4544
	ds_read_b128 v[180:183], v232 offset:8704
	ds_read_b128 v[184:187], v232 offset:8768
	ds_read_b128 v[188:191], v232 offset:8832
	ds_read_b128 v[200:203], v232 offset:8896
	s_waitcnt lgkmcnt(8)
	v_mfma_f32_16x16x32_bf16 v[4:7], v[132:135], v[84:87], 0
	v_mfma_f32_16x16x32_bf16 v[4:7], v[136:139], v[88:91], v[4:7]
	v_mfma_f32_16x16x32_bf16 v[4:7], v[140:143], v[92:95], v[4:7]
	v_mfma_f32_16x16x32_bf16 v[4:7], v[144:147], v[96:99], v[4:7]
	ds_read_b128 v[132:135], v232 offset:13056
	ds_read_b128 v[136:139], v232 offset:13120
	ds_read_b128 v[140:143], v232 offset:13184
	ds_read_b128 v[144:147], v232 offset:13248
	s_waitcnt lgkmcnt(8)
	v_mfma_f32_16x16x32_bf16 v[8:11], v[148:151], v[84:87], 0
	v_mfma_f32_16x16x32_bf16 v[8:11], v[152:155], v[88:91], v[8:11]
	v_mfma_f32_16x16x32_bf16 v[8:11], v[172:175], v[92:95], v[8:11]
	v_mfma_f32_16x16x32_bf16 v[8:11], v[176:179], v[96:99], v[8:11]
	ds_read_b128 v[148:151], v232 offset:17408
	ds_read_b128 v[152:155], v232 offset:17472
	ds_read_b128 v[172:175], v232 offset:17536
	ds_read_b128 v[176:179], v232 offset:17600
	s_waitcnt lgkmcnt(8)
	v_mfma_f32_16x16x32_bf16 v[12:15], v[180:183], v[84:87], 0
	v_mfma_f32_16x16x32_bf16 v[12:15], v[184:187], v[88:91], v[12:15]
	v_mfma_f32_16x16x32_bf16 v[12:15], v[188:191], v[92:95], v[12:15]
	v_mfma_f32_16x16x32_bf16 v[12:15], v[200:203], v[96:99], v[12:15]
	ds_read_b128 v[180:183], v232 offset:21760
	ds_read_b128 v[184:187], v232 offset:21824
	ds_read_b128 v[188:191], v232 offset:21888
	ds_read_b128 v[200:203], v232 offset:21952
	s_waitcnt lgkmcnt(8)
	v_mfma_f32_16x16x32_bf16 v[16:19], v[132:135], v[84:87], 0
	v_mfma_f32_16x16x32_bf16 v[16:19], v[136:139], v[88:91], v[16:19]
	v_mfma_f32_16x16x32_bf16 v[16:19], v[140:143], v[92:95], v[16:19]
	v_mfma_f32_16x16x32_bf16 v[16:19], v[144:147], v[96:99], v[16:19]
	ds_read_b128 v[132:135], v232 offset:26112
	ds_read_b128 v[136:139], v232 offset:26176
	ds_read_b128 v[140:143], v232 offset:26240
	ds_read_b128 v[144:147], v232 offset:26304
	s_waitcnt lgkmcnt(8)
	v_mfma_f32_16x16x32_bf16 v[20:23], v[148:151], v[84:87], 0
	v_mfma_f32_16x16x32_bf16 v[20:23], v[152:155], v[88:91], v[20:23]
	v_mfma_f32_16x16x32_bf16 v[20:23], v[172:175], v[92:95], v[20:23]
	v_mfma_f32_16x16x32_bf16 v[20:23], v[176:179], v[96:99], v[20:23]
	ds_read_b128 v[148:151], v232 offset:30464
	ds_read_b128 v[152:155], v232 offset:30528
	ds_read_b128 v[172:175], v232 offset:30592
	ds_read_b128 v[176:179], v232 offset:30656
	s_waitcnt lgkmcnt(8)
	v_mfma_f32_16x16x32_bf16 v[24:27], v[180:183], v[84:87], 0
	v_mfma_f32_16x16x32_bf16 v[24:27], v[184:187], v[88:91], v[24:27]
	v_mfma_f32_16x16x32_bf16 v[24:27], v[188:191], v[92:95], v[24:27]
	v_mfma_f32_16x16x32_bf16 v[24:27], v[200:203], v[96:99], v[24:27]
	s_waitcnt lgkmcnt(4)
	v_mfma_f32_16x16x32_bf16 v[28:31], v[132:135], v[84:87], 0
	v_mfma_f32_16x16x32_bf16 v[28:31], v[136:139], v[88:91], v[28:31]
	v_mfma_f32_16x16x32_bf16 v[28:31], v[140:143], v[92:95], v[28:31]
	v_mfma_f32_16x16x32_bf16 v[28:31], v[144:147], v[96:99], v[28:31]
	s_waitcnt lgkmcnt(0)
	v_mfma_f32_16x16x32_bf16 v[32:35], v[148:151], v[84:87], 0
	v_mfma_f32_16x16x32_bf16 v[32:35], v[152:155], v[88:91], v[32:35]
	v_mfma_f32_16x16x32_bf16 v[32:35], v[172:175], v[92:95], v[32:35]
	v_mfma_f32_16x16x32_bf16 v[32:35], v[176:179], v[96:99], v[32:35]
	s_branch .Lfix_mmdone_ta

.Lfix_mmdone_ta:
	s_waitcnt vmcnt(36)
	v_lshlrev_b32_e32 v220, 16, v100
	v_and_b32_e32 v221, 0xffff0000, v100
	v_lshlrev_b32_e32 v222, 16, v101
	v_and_b32_e32 v223, 0xffff0000, v101
	v_pk_add_f32 v[4:5], v[4:5], v[220:221]
	v_pk_add_f32 v[6:7], v[6:7], v[222:223]
	v_pk_mul_f32 v[224:225], v[4:5], v[4:5]
	v_pk_fma_f32 v[224:225], v[6:7], v[6:7], v[224:225]
	v_lshlrev_b32_e32 v220, 16, v102
	v_and_b32_e32 v221, 0xffff0000, v102
	v_lshlrev_b32_e32 v222, 16, v103
	v_and_b32_e32 v223, 0xffff0000, v103
	v_pk_add_f32 v[8:9], v[8:9], v[220:221]
	v_pk_add_f32 v[10:11], v[10:11], v[222:223]
	v_pk_fma_f32 v[224:225], v[8:9], v[8:9], v[224:225]
	v_pk_fma_f32 v[224:225], v[10:11], v[10:11], v[224:225]
	v_lshlrev_b32_e32 v220, 16, v104
	v_and_b32_e32 v221, 0xffff0000, v104
	v_lshlrev_b32_e32 v222, 16, v105
	v_and_b32_e32 v223, 0xffff0000, v105
	v_pk_add_f32 v[12:13], v[12:13], v[220:221]
	v_pk_add_f32 v[14:15], v[14:15], v[222:223]
	v_pk_fma_f32 v[224:225], v[12:13], v[12:13], v[224:225]
	v_pk_fma_f32 v[224:225], v[14:15], v[14:15], v[224:225]
	v_lshlrev_b32_e32 v220, 16, v106
	v_and_b32_e32 v221, 0xffff0000, v106
	v_lshlrev_b32_e32 v222, 16, v107
	v_and_b32_e32 v223, 0xffff0000, v107
	v_pk_add_f32 v[16:17], v[16:17], v[220:221]
	v_pk_add_f32 v[18:19], v[18:19], v[222:223]
	v_pk_fma_f32 v[224:225], v[16:17], v[16:17], v[224:225]
	v_pk_fma_f32 v[224:225], v[18:19], v[18:19], v[224:225]
	v_lshlrev_b32_e32 v220, 16, v108
	v_and_b32_e32 v221, 0xffff0000, v108
	v_lshlrev_b32_e32 v222, 16, v109
	v_and_b32_e32 v223, 0xffff0000, v109
	v_pk_add_f32 v[20:21], v[20:21], v[220:221]
	v_pk_add_f32 v[22:23], v[22:23], v[222:223]
	v_pk_fma_f32 v[224:225], v[20:21], v[20:21], v[224:225]
	v_pk_fma_f32 v[224:225], v[22:23], v[22:23], v[224:225]
	v_lshlrev_b32_e32 v220, 16, v110
	v_and_b32_e32 v221, 0xffff0000, v110
	v_lshlrev_b32_e32 v222, 16, v111
	v_and_b32_e32 v223, 0xffff0000, v111
	v_pk_add_f32 v[24:25], v[24:25], v[220:221]
	v_pk_add_f32 v[26:27], v[26:27], v[222:223]
	v_pk_fma_f32 v[224:225], v[24:25], v[24:25], v[224:225]
	v_pk_fma_f32 v[224:225], v[26:27], v[26:27], v[224:225]
	v_lshlrev_b32_e32 v220, 16, v112
	v_and_b32_e32 v221, 0xffff0000, v112
	v_lshlrev_b32_e32 v222, 16, v113
	v_and_b32_e32 v223, 0xffff0000, v113
	v_pk_add_f32 v[28:29], v[28:29], v[220:221]
	v_pk_add_f32 v[30:31], v[30:31], v[222:223]
	v_pk_fma_f32 v[224:225], v[28:29], v[28:29], v[224:225]
	v_pk_fma_f32 v[224:225], v[30:31], v[30:31], v[224:225]
	v_lshlrev_b32_e32 v220, 16, v114
	v_and_b32_e32 v221, 0xffff0000, v114
	v_lshlrev_b32_e32 v222, 16, v115
	v_and_b32_e32 v223, 0xffff0000, v115
	v_pk_add_f32 v[32:33], v[32:33], v[220:221]
	v_pk_add_f32 v[34:35], v[34:35], v[222:223]
	v_pk_fma_f32 v[224:225], v[32:33], v[32:33], v[224:225]
	v_pk_fma_f32 v[224:225], v[34:35], v[34:35], v[224:225]
	v_add_f32_e32 v226, v224, v225
	ds_bpermute_b32 v227, v233, v226
	s_waitcnt lgkmcnt(0)
	v_add_f32_e32 v226, v226, v227
	ds_bpermute_b32 v227, v234, v226
	s_waitcnt lgkmcnt(0)
	v_add_f32_e32 v226, v226, v227
	v_fmamk_f32 v226, v226, 0x3c000000, v195
	v_rsq_f32_e32 v228, v226
	s_nop 0
	s_waitcnt vmcnt(28)
	v_pk_mul_f32 v[4:5], v[4:5], v[228:229] op_sel_hi:[1,0]
	v_pk_mul_f32 v[6:7], v[6:7], v[228:229] op_sel_hi:[1,0]
	v_lshlrev_b32_e32 v220, 16, v116
	v_and_b32_e32 v221, 0xffff0000, v116
	v_lshlrev_b32_e32 v222, 16, v117
	v_and_b32_e32 v223, 0xffff0000, v117
	v_pk_mul_f32 v[4:5], v[4:5], v[220:221]
	v_pk_mul_f32 v[6:7], v[6:7], v[222:223]
	v_cvt_pk_bf16_f32 v116, v4, v5
	v_cvt_pk_bf16_f32 v117, v6, v7
	global_store_dwordx2 v2, v[116:117], s[10:11]
	v_pk_mul_f32 v[8:9], v[8:9], v[228:229] op_sel_hi:[1,0]
	v_pk_mul_f32 v[10:11], v[10:11], v[228:229] op_sel_hi:[1,0]
	v_lshlrev_b32_e32 v220, 16, v118
	v_and_b32_e32 v221, 0xffff0000, v118
	v_lshlrev_b32_e32 v222, 16, v119
	v_and_b32_e32 v223, 0xffff0000, v119
	v_pk_mul_f32 v[8:9], v[8:9], v[220:221]
	v_pk_mul_f32 v[10:11], v[10:11], v[222:223]
	v_cvt_pk_bf16_f32 v118, v8, v9
	v_cvt_pk_bf16_f32 v119, v10, v11
	global_store_dwordx2 v2, v[118:119], s[10:11] offset:32
	v_pk_mul_f32 v[12:13], v[12:13], v[228:229] op_sel_hi:[1,0]
	v_pk_mul_f32 v[14:15], v[14:15], v[228:229] op_sel_hi:[1,0]
	v_lshlrev_b32_e32 v220, 16, v120
	v_and_b32_e32 v221, 0xffff0000, v120
	v_lshlrev_b32_e32 v222, 16, v121
	v_and_b32_e32 v223, 0xffff0000, v121
	v_pk_mul_f32 v[12:13], v[12:13], v[220:221]
	v_pk_mul_f32 v[14:15], v[14:15], v[222:223]
	v_cvt_pk_bf16_f32 v120, v12, v13
	v_cvt_pk_bf16_f32 v121, v14, v15
	global_store_dwordx2 v2, v[120:121], s[10:11] offset:64
	v_pk_mul_f32 v[16:17], v[16:17], v[228:229] op_sel_hi:[1,0]
	v_pk_mul_f32 v[18:19], v[18:19], v[228:229] op_sel_hi:[1,0]
	v_lshlrev_b32_e32 v220, 16, v122
	v_and_b32_e32 v221, 0xffff0000, v122
	v_lshlrev_b32_e32 v222, 16, v123
	v_and_b32_e32 v223, 0xffff0000, v123
	v_pk_mul_f32 v[16:17], v[16:17], v[220:221]
	v_pk_mul_f32 v[18:19], v[18:19], v[222:223]
	v_cvt_pk_bf16_f32 v122, v16, v17
	v_cvt_pk_bf16_f32 v123, v18, v19
	global_store_dwordx2 v2, v[122:123], s[10:11] offset:96
	v_pk_mul_f32 v[20:21], v[20:21], v[228:229] op_sel_hi:[1,0]
	v_pk_mul_f32 v[22:23], v[22:23], v[228:229] op_sel_hi:[1,0]
	v_lshlrev_b32_e32 v220, 16, v124
	v_and_b32_e32 v221, 0xffff0000, v124
	v_lshlrev_b32_e32 v222, 16, v125
	v_and_b32_e32 v223, 0xffff0000, v125
	v_pk_mul_f32 v[20:21], v[20:21], v[220:221]
	v_pk_mul_f32 v[22:23], v[22:23], v[222:223]
	v_cvt_pk_bf16_f32 v124, v20, v21
	v_cvt_pk_bf16_f32 v125, v22, v23
	global_store_dwordx2 v2, v[124:125], s[10:11] offset:128
	v_pk_mul_f32 v[24:25], v[24:25], v[228:229] op_sel_hi:[1,0]
	v_pk_mul_f32 v[26:27], v[26:27], v[228:229] op_sel_hi:[1,0]
	v_lshlrev_b32_e32 v220, 16, v126
	v_and_b32_e32 v221, 0xffff0000, v126
	v_lshlrev_b32_e32 v222, 16, v127
	v_and_b32_e32 v223, 0xffff0000, v127
	v_pk_mul_f32 v[24:25], v[24:25], v[220:221]
	v_pk_mul_f32 v[26:27], v[26:27], v[222:223]
	v_cvt_pk_bf16_f32 v126, v24, v25
	v_cvt_pk_bf16_f32 v127, v26, v27
	global_store_dwordx2 v2, v[126:127], s[10:11] offset:160
	v_pk_mul_f32 v[28:29], v[28:29], v[228:229] op_sel_hi:[1,0]
	v_pk_mul_f32 v[30:31], v[30:31], v[228:229] op_sel_hi:[1,0]
	v_lshlrev_b32_e32 v220, 16, v128
	v_and_b32_e32 v221, 0xffff0000, v128
	v_lshlrev_b32_e32 v222, 16, v129
	v_and_b32_e32 v223, 0xffff0000, v129
	v_pk_mul_f32 v[28:29], v[28:29], v[220:221]
	v_pk_mul_f32 v[30:31], v[30:31], v[222:223]
	v_cvt_pk_bf16_f32 v128, v28, v29
	v_cvt_pk_bf16_f32 v129, v30, v31
	global_store_dwordx2 v2, v[128:129], s[10:11] offset:192
	v_pk_mul_f32 v[32:33], v[32:33], v[228:229] op_sel_hi:[1,0]
	v_pk_mul_f32 v[34:35], v[34:35], v[228:229] op_sel_hi:[1,0]
	v_lshlrev_b32_e32 v220, 16, v130
	v_and_b32_e32 v221, 0xffff0000, v130
	v_lshlrev_b32_e32 v222, 16, v131
	v_and_b32_e32 v223, 0xffff0000, v131
	v_pk_mul_f32 v[32:33], v[32:33], v[220:221]
	v_pk_mul_f32 v[34:35], v[34:35], v[222:223]
	v_cvt_pk_bf16_f32 v130, v32, v33
	v_cvt_pk_bf16_f32 v131, v34, v35
	global_store_dwordx2 v2, v[130:131], s[10:11] offset:224
	s_add_u32 s10, s10, 0x8000
	s_addc_u32 s11, s11, 0
	global_load_dwordx4 v[84:87], v0, s[4:5]
	global_load_dwordx4 v[88:91], v0, s[4:5] offset:64
	global_load_dwordx4 v[92:95], v0, s[4:5] offset:128
	global_load_dwordx4 v[96:99], v0, s[4:5] offset:192
	global_load_dwordx2 v[100:101], v2, s[8:9]
	global_load_dwordx2 v[102:103], v2, s[8:9] offset:32
	global_load_dwordx2 v[104:105], v2, s[8:9] offset:64
	global_load_dwordx2 v[106:107], v2, s[8:9] offset:96
	global_load_dwordx2 v[108:109], v2, s[8:9] offset:128
	global_load_dwordx2 v[110:111], v2, s[8:9] offset:160
	global_load_dwordx2 v[112:113], v2, s[8:9] offset:192
	global_load_dwordx2 v[114:115], v2, s[8:9] offset:224
	global_load_dwordx2 v[116:117], v1, s[6:7]
	global_load_dwordx2 v[118:119], v1, s[6:7] offset:32
	global_load_dwordx2 v[120:121], v1, s[6:7] offset:64
	global_load_dwordx2 v[122:123], v1, s[6:7] offset:96
	global_load_dwordx2 v[124:125], v1, s[6:7] offset:128
	global_load_dwordx2 v[126:127], v1, s[6:7] offset:160
	global_load_dwordx2 v[128:129], v1, s[6:7] offset:192
	global_load_dwordx2 v[130:131], v1, s[6:7] offset:224
	s_add_u32 s4, s4, 0x6000
	s_addc_u32 s5, s5, 0
	s_add_u32 s6, s6, 0x6000
	s_addc_u32 s7, s7, 0
	s_add_u32 s8, s8, 0x8000
	s_addc_u32 s9, s9, 0
	s_cmp_eq_u32 s40, 0
	s_cbranch_scc1 .Lfix_nomm_tb
	s_waitcnt vmcnt(44)
	ds_read_b128 v[132:135], v232 offset:0
	ds_read_b128 v[136:139], v232 offset:64
	ds_read_b128 v[140:143], v232 offset:128
	ds_read_b128 v[144:147], v232 offset:192
	ds_read_b128 v[148:151], v232 offset:4352
	ds_read_b128 v[152:155], v232 offset:4416
	ds_read_b128 v[172:175], v232 offset:4480
	ds_read_b128 v[176:179], v232 offset:4544
	ds_read_b128 v[180:183], v232 offset:8704
	ds_read_b128 v[184:187], v232 offset:8768
	ds_read_b128 v[188:191], v232 offset:8832
	ds_read_b128 v[200:203], v232 offset:8896
	s_waitcnt lgkmcnt(8)
	v_mfma_f32_16x16x32_bf16 v[4:7], v[132:135], v[36:39], 0
	v_mfma_f32_16x16x32_bf16 v[4:7], v[136:139], v[40:43], v[4:7]
	v_mfma_f32_16x16x32_bf16 v[4:7], v[140:143], v[44:47], v[4:7]
	v_mfma_f32_16x16x32_bf16 v[4:7], v[144:147], v[48:51], v[4:7]
	ds_read_b128 v[132:135], v232 offset:13056
	ds_read_b128 v[136:139], v232 offset:13120
	ds_read_b128 v[140:143], v232 offset:13184
	ds_read_b128 v[144:147], v232 offset:13248
	s_waitcnt lgkmcnt(8)
	v_mfma_f32_16x16x32_bf16 v[8:11], v[148:151], v[36:39], 0
	v_mfma_f32_16x16x32_bf16 v[8:11], v[152:155], v[40:43], v[8:11]
	v_mfma_f32_16x16x32_bf16 v[8:11], v[172:175], v[44:47], v[8:11]
	v_mfma_f32_16x16x32_bf16 v[8:11], v[176:179], v[48:51], v[8:11]
	ds_read_b128 v[148:151], v232 offset:17408
	ds_read_b128 v[152:155], v232 offset:17472
	ds_read_b128 v[172:175], v232 offset:17536
	ds_read_b128 v[176:179], v232 offset:17600
	s_waitcnt lgkmcnt(8)
	v_mfma_f32_16x16x32_bf16 v[12:15], v[180:183], v[36:39], 0
	v_mfma_f32_16x16x32_bf16 v[12:15], v[184:187], v[40:43], v[12:15]
	v_mfma_f32_16x16x32_bf16 v[12:15], v[188:191], v[44:47], v[12:15]
	v_mfma_f32_16x16x32_bf16 v[12:15], v[200:203], v[48:51], v[12:15]
	ds_read_b128 v[180:183], v232 offset:21760
	ds_read_b128 v[184:187], v232 offset:21824
	ds_read_b128 v[188:191], v232 offset:21888
	ds_read_b128 v[200:203], v232 offset:21952
	s_waitcnt lgkmcnt(8)
	v_mfma_f32_16x16x32_bf16 v[16:19], v[132:135], v[36:39], 0
	v_mfma_f32_16x16x32_bf16 v[16:19], v[136:139], v[40:43], v[16:19]
	v_mfma_f32_16x16x32_bf16 v[16:19], v[140:143], v[44:47], v[16:19]
	v_mfma_f32_16x16x32_bf16 v[16:19], v[144:147], v[48:51], v[16:19]
	ds_read_b128 v[132:135], v232 offset:26112
	ds_read_b128 v[136:139], v232 offset:26176
	ds_read_b128 v[140:143], v232 offset:26240
	ds_read_b128 v[144:147], v232 offset:26304
	s_waitcnt lgkmcnt(8)
	v_mfma_f32_16x16x32_bf16 v[20:23], v[148:151], v[36:39], 0
	v_mfma_f32_16x16x32_bf16 v[20:23], v[152:155], v[40:43], v[20:23]
	v_mfma_f32_16x16x32_bf16 v[20:23], v[172:175], v[44:47], v[20:23]
	v_mfma_f32_16x16x32_bf16 v[20:23], v[176:179], v[48:51], v[20:23]
	ds_read_b128 v[148:151], v232 offset:30464
	ds_read_b128 v[152:155], v232 offset:30528
	ds_read_b128 v[172:175], v232 offset:30592
	ds_read_b128 v[176:179], v232 offset:30656
	s_waitcnt lgkmcnt(8)
	v_mfma_f32_16x16x32_bf16 v[24:27], v[180:183], v[36:39], 0
	v_mfma_f32_16x16x32_bf16 v[24:27], v[184:187], v[40:43], v[24:27]
	v_mfma_f32_16x16x32_bf16 v[24:27], v[188:191], v[44:47], v[24:27]
	v_mfma_f32_16x16x32_bf16 v[24:27], v[200:203], v[48:51], v[24:27]
	s_waitcnt lgkmcnt(4)
	v_mfma_f32_16x16x32_bf16 v[28:31], v[132:135], v[36:39], 0
	v_mfma_f32_16x16x32_bf16 v[28:31], v[136:139], v[40:43], v[28:31]
	v_mfma_f32_16x16x32_bf16 v[28:31], v[140:143], v[44:47], v[28:31]
	v_mfma_f32_16x16x32_bf16 v[28:31], v[144:147], v[48:51], v[28:31]
	s_waitcnt lgkmcnt(0)
	v_mfma_f32_16x16x32_bf16 v[32:35], v[148:151], v[36:39], 0
	v_mfma_f32_16x16x32_bf16 v[32:35], v[152:155], v[40:43], v[32:35]
	v_mfma_f32_16x16x32_bf16 v[32:35], v[172:175], v[44:47], v[32:35]
	v_mfma_f32_16x16x32_bf16 v[32:35], v[176:179], v[48:51], v[32:35]
	s_branch .Lfix_mmdone_tb

.Lfix_mmdone_tb:
	s_waitcnt vmcnt(36)
	v_lshlrev_b32_e32 v220, 16, v52
	v_and_b32_e32 v221, 0xffff0000, v52
	v_lshlrev_b32_e32 v222, 16, v53
	v_and_b32_e32 v223, 0xffff0000, v53
	v_pk_add_f32 v[4:5], v[4:5], v[220:221]
	v_pk_add_f32 v[6:7], v[6:7], v[222:223]
	v_pk_mul_f32 v[224:225], v[4:5], v[4:5]
	v_pk_fma_f32 v[224:225], v[6:7], v[6:7], v[224:225]
	v_lshlrev_b32_e32 v220, 16, v54
	v_and_b32_e32 v221, 0xffff0000, v54
	v_lshlrev_b32_e32 v222, 16, v55
	v_and_b32_e32 v223, 0xffff0000, v55
	v_pk_add_f32 v[8:9], v[8:9], v[220:221]
	v_pk_add_f32 v[10:11], v[10:11], v[222:223]
	v_pk_fma_f32 v[224:225], v[8:9], v[8:9], v[224:225]
	v_pk_fma_f32 v[224:225], v[10:11], v[10:11], v[224:225]
	v_lshlrev_b32_e32 v220, 16, v56
	v_and_b32_e32 v221, 0xffff0000, v56
	v_lshlrev_b32_e32 v222, 16, v57
	v_and_b32_e32 v223, 0xffff0000, v57
	v_pk_add_f32 v[12:13], v[12:13], v[220:221]
	v_pk_add_f32 v[14:15], v[14:15], v[222:223]
	v_pk_fma_f32 v[224:225], v[12:13], v[12:13], v[224:225]
	v_pk_fma_f32 v[224:225], v[14:15], v[14:15], v[224:225]
	v_lshlrev_b32_e32 v220, 16, v58
	v_and_b32_e32 v221, 0xffff0000, v58
	v_lshlrev_b32_e32 v222, 16, v59
	v_and_b32_e32 v223, 0xffff0000, v59
	v_pk_add_f32 v[16:17], v[16:17], v[220:221]
	v_pk_add_f32 v[18:19], v[18:19], v[222:223]
	v_pk_fma_f32 v[224:225], v[16:17], v[16:17], v[224:225]
	v_pk_fma_f32 v[224:225], v[18:19], v[18:19], v[224:225]
	v_lshlrev_b32_e32 v220, 16, v60
	v_and_b32_e32 v221, 0xffff0000, v60
	v_lshlrev_b32_e32 v222, 16, v61
	v_and_b32_e32 v223, 0xffff0000, v61
	v_pk_add_f32 v[20:21], v[20:21], v[220:221]
	v_pk_add_f32 v[22:23], v[22:23], v[222:223]
	v_pk_fma_f32 v[224:225], v[20:21], v[20:21], v[224:225]
	v_pk_fma_f32 v[224:225], v[22:23], v[22:23], v[224:225]
	v_lshlrev_b32_e32 v220, 16, v62
	v_and_b32_e32 v221, 0xffff0000, v62
	v_lshlrev_b32_e32 v222, 16, v63
	v_and_b32_e32 v223, 0xffff0000, v63
	v_pk_add_f32 v[24:25], v[24:25], v[220:221]
	v_pk_add_f32 v[26:27], v[26:27], v[222:223]
	v_pk_fma_f32 v[224:225], v[24:25], v[24:25], v[224:225]
	v_pk_fma_f32 v[224:225], v[26:27], v[26:27], v[224:225]
	v_lshlrev_b32_e32 v220, 16, v64
	v_and_b32_e32 v221, 0xffff0000, v64
	v_lshlrev_b32_e32 v222, 16, v65
	v_and_b32_e32 v223, 0xffff0000, v65
	v_pk_add_f32 v[28:29], v[28:29], v[220:221]
	v_pk_add_f32 v[30:31], v[30:31], v[222:223]
	v_pk_fma_f32 v[224:225], v[28:29], v[28:29], v[224:225]
	v_pk_fma_f32 v[224:225], v[30:31], v[30:31], v[224:225]
	v_lshlrev_b32_e32 v220, 16, v66
	v_and_b32_e32 v221, 0xffff0000, v66
	v_lshlrev_b32_e32 v222, 16, v67
	v_and_b32_e32 v223, 0xffff0000, v67
	v_pk_add_f32 v[32:33], v[32:33], v[220:221]
	v_pk_add_f32 v[34:35], v[34:35], v[222:223]
	v_pk_fma_f32 v[224:225], v[32:33], v[32:33], v[224:225]
	v_pk_fma_f32 v[224:225], v[34:35], v[34:35], v[224:225]
	v_add_f32_e32 v226, v224, v225
	ds_bpermute_b32 v227, v233, v226
	s_waitcnt lgkmcnt(0)
	v_add_f32_e32 v226, v226, v227
	ds_bpermute_b32 v227, v234, v226
	s_waitcnt lgkmcnt(0)
	v_add_f32_e32 v226, v226, v227
	v_fmamk_f32 v226, v226, 0x3c000000, v195
	v_rsq_f32_e32 v228, v226
	s_nop 0
	s_waitcnt vmcnt(28)
	v_pk_mul_f32 v[4:5], v[4:5], v[228:229] op_sel_hi:[1,0]
	v_pk_mul_f32 v[6:7], v[6:7], v[228:229] op_sel_hi:[1,0]
	v_lshlrev_b32_e32 v220, 16, v68
	v_and_b32_e32 v221, 0xffff0000, v68
	v_lshlrev_b32_e32 v222, 16, v69
	v_and_b32_e32 v223, 0xffff0000, v69
	v_pk_mul_f32 v[4:5], v[4:5], v[220:221]
	v_pk_mul_f32 v[6:7], v[6:7], v[222:223]
	v_cvt_pk_bf16_f32 v68, v4, v5
	v_cvt_pk_bf16_f32 v69, v6, v7
	global_store_dwordx2 v2, v[68:69], s[10:11]
	v_pk_mul_f32 v[8:9], v[8:9], v[228:229] op_sel_hi:[1,0]
	v_pk_mul_f32 v[10:11], v[10:11], v[228:229] op_sel_hi:[1,0]
	v_lshlrev_b32_e32 v220, 16, v70
	v_and_b32_e32 v221, 0xffff0000, v70
	v_lshlrev_b32_e32 v222, 16, v71
	v_and_b32_e32 v223, 0xffff0000, v71
	v_pk_mul_f32 v[8:9], v[8:9], v[220:221]
	v_pk_mul_f32 v[10:11], v[10:11], v[222:223]
	v_cvt_pk_bf16_f32 v70, v8, v9
	v_cvt_pk_bf16_f32 v71, v10, v11
	global_store_dwordx2 v2, v[70:71], s[10:11] offset:32
	v_pk_mul_f32 v[12:13], v[12:13], v[228:229] op_sel_hi:[1,0]
	v_pk_mul_f32 v[14:15], v[14:15], v[228:229] op_sel_hi:[1,0]
	v_lshlrev_b32_e32 v220, 16, v72
	v_and_b32_e32 v221, 0xffff0000, v72
	v_lshlrev_b32_e32 v222, 16, v73
	v_and_b32_e32 v223, 0xffff0000, v73
	v_pk_mul_f32 v[12:13], v[12:13], v[220:221]
	v_pk_mul_f32 v[14:15], v[14:15], v[222:223]
	v_cvt_pk_bf16_f32 v72, v12, v13
	v_cvt_pk_bf16_f32 v73, v14, v15
	global_store_dwordx2 v2, v[72:73], s[10:11] offset:64
	v_pk_mul_f32 v[16:17], v[16:17], v[228:229] op_sel_hi:[1,0]
	v_pk_mul_f32 v[18:19], v[18:19], v[228:229] op_sel_hi:[1,0]
	v_lshlrev_b32_e32 v220, 16, v74
	v_and_b32_e32 v221, 0xffff0000, v74
	v_lshlrev_b32_e32 v222, 16, v75
	v_and_b32_e32 v223, 0xffff0000, v75
	v_pk_mul_f32 v[16:17], v[16:17], v[220:221]
	v_pk_mul_f32 v[18:19], v[18:19], v[222:223]
	v_cvt_pk_bf16_f32 v74, v16, v17
	v_cvt_pk_bf16_f32 v75, v18, v19
	global_store_dwordx2 v2, v[74:75], s[10:11] offset:96
	v_pk_mul_f32 v[20:21], v[20:21], v[228:229] op_sel_hi:[1,0]
	v_pk_mul_f32 v[22:23], v[22:23], v[228:229] op_sel_hi:[1,0]
	v_lshlrev_b32_e32 v220, 16, v76
	v_and_b32_e32 v221, 0xffff0000, v76
	v_lshlrev_b32_e32 v222, 16, v77
	v_and_b32_e32 v223, 0xffff0000, v77
	v_pk_mul_f32 v[20:21], v[20:21], v[220:221]
	v_pk_mul_f32 v[22:23], v[22:23], v[222:223]
	v_cvt_pk_bf16_f32 v76, v20, v21
	v_cvt_pk_bf16_f32 v77, v22, v23
	global_store_dwordx2 v2, v[76:77], s[10:11] offset:128
	v_pk_mul_f32 v[24:25], v[24:25], v[228:229] op_sel_hi:[1,0]
	v_pk_mul_f32 v[26:27], v[26:27], v[228:229] op_sel_hi:[1,0]
	v_lshlrev_b32_e32 v220, 16, v78
	v_and_b32_e32 v221, 0xffff0000, v78
	v_lshlrev_b32_e32 v222, 16, v79
	v_and_b32_e32 v223, 0xffff0000, v79
	v_pk_mul_f32 v[24:25], v[24:25], v[220:221]
	v_pk_mul_f32 v[26:27], v[26:27], v[222:223]
	v_cvt_pk_bf16_f32 v78, v24, v25
	v_cvt_pk_bf16_f32 v79, v26, v27
	global_store_dwordx2 v2, v[78:79], s[10:11] offset:160
	v_pk_mul_f32 v[28:29], v[28:29], v[228:229] op_sel_hi:[1,0]
	v_pk_mul_f32 v[30:31], v[30:31], v[228:229] op_sel_hi:[1,0]
	v_lshlrev_b32_e32 v220, 16, v80
	v_and_b32_e32 v221, 0xffff0000, v80
	v_lshlrev_b32_e32 v222, 16, v81
	v_and_b32_e32 v223, 0xffff0000, v81
	v_pk_mul_f32 v[28:29], v[28:29], v[220:221]
	v_pk_mul_f32 v[30:31], v[30:31], v[222:223]
	v_cvt_pk_bf16_f32 v80, v28, v29
	v_cvt_pk_bf16_f32 v81, v30, v31
	global_store_dwordx2 v2, v[80:81], s[10:11] offset:192
	v_pk_mul_f32 v[32:33], v[32:33], v[228:229] op_sel_hi:[1,0]
	v_pk_mul_f32 v[34:35], v[34:35], v[228:229] op_sel_hi:[1,0]
	v_lshlrev_b32_e32 v220, 16, v82
	v_and_b32_e32 v221, 0xffff0000, v82
	v_lshlrev_b32_e32 v222, 16, v83
	v_and_b32_e32 v223, 0xffff0000, v83
	v_pk_mul_f32 v[32:33], v[32:33], v[220:221]
	v_pk_mul_f32 v[34:35], v[34:35], v[222:223]
	v_cvt_pk_bf16_f32 v82, v32, v33
	v_cvt_pk_bf16_f32 v83, v34, v35
	global_store_dwordx2 v2, v[82:83], s[10:11] offset:224
	s_add_u32 s10, s10, 0x8000
	s_addc_u32 s11, s11, 0
	s_add_i32 s13, s13, -1
	s_cmp_lg_u32 s13, 0
	s_cbranch_scc1 .Lfix_loop
	s_cmp_eq_u32 s40, 0
	s_cbranch_scc1 .Lfix_nomm_t7
	s_waitcnt vmcnt(24)
	ds_read_b128 v[132:135], v232 offset:0
	ds_read_b128 v[136:139], v232 offset:64
	ds_read_b128 v[140:143], v232 offset:128
	ds_read_b128 v[144:147], v232 offset:192
	ds_read_b128 v[148:151], v232 offset:4352
	ds_read_b128 v[152:155], v232 offset:4416
	ds_read_b128 v[172:175], v232 offset:4480
	ds_read_b128 v[176:179], v232 offset:4544
	ds_read_b128 v[180:183], v232 offset:8704
	ds_read_b128 v[184:187], v232 offset:8768
	ds_read_b128 v[188:191], v232 offset:8832
	ds_read_b128 v[200:203], v232 offset:8896
	s_waitcnt lgkmcnt(8)
	v_mfma_f32_16x16x32_bf16 v[4:7], v[132:135], v[84:87], 0
	v_mfma_f32_16x16x32_bf16 v[4:7], v[136:139], v[88:91], v[4:7]
	v_mfma_f32_16x16x32_bf16 v[4:7], v[140:143], v[92:95], v[4:7]
	v_mfma_f32_16x16x32_bf16 v[4:7], v[144:147], v[96:99], v[4:7]
	ds_read_b128 v[132:135], v232 offset:13056
	ds_read_b128 v[136:139], v232 offset:13120
	ds_read_b128 v[140:143], v232 offset:13184
	ds_read_b128 v[144:147], v232 offset:13248
	s_waitcnt lgkmcnt(8)
	v_mfma_f32_16x16x32_bf16 v[8:11], v[148:151], v[84:87], 0
	v_mfma_f32_16x16x32_bf16 v[8:11], v[152:155], v[88:91], v[8:11]
	v_mfma_f32_16x16x32_bf16 v[8:11], v[172:175], v[92:95], v[8:11]
	v_mfma_f32_16x16x32_bf16 v[8:11], v[176:179], v[96:99], v[8:11]
	ds_read_b128 v[148:151], v232 offset:17408
	ds_read_b128 v[152:155], v232 offset:17472
	ds_read_b128 v[172:175], v232 offset:17536
	ds_read_b128 v[176:179], v232 offset:17600
	s_waitcnt lgkmcnt(8)
	v_mfma_f32_16x16x32_bf16 v[12:15], v[180:183], v[84:87], 0
	v_mfma_f32_16x16x32_bf16 v[12:15], v[184:187], v[88:91], v[12:15]
	v_mfma_f32_16x16x32_bf16 v[12:15], v[188:191], v[92:95], v[12:15]
	v_mfma_f32_16x16x32_bf16 v[12:15], v[200:203], v[96:99], v[12:15]
	ds_read_b128 v[180:183], v232 offset:21760
	ds_read_b128 v[184:187], v232 offset:21824
	ds_read_b128 v[188:191], v232 offset:21888
	ds_read_b128 v[200:203], v232 offset:21952
	s_waitcnt lgkmcnt(8)
	v_mfma_f32_16x16x32_bf16 v[16:19], v[132:135], v[84:87], 0
	v_mfma_f32_16x16x32_bf16 v[16:19], v[136:139], v[88:91], v[16:19]
	v_mfma_f32_16x16x32_bf16 v[16:19], v[140:143], v[92:95], v[16:19]
	v_mfma_f32_16x16x32_bf16 v[16:19], v[144:147], v[96:99], v[16:19]
	ds_read_b128 v[132:135], v232 offset:26112
	ds_read_b128 v[136:139], v232 offset:26176
	ds_read_b128 v[140:143], v232 offset:26240
	ds_read_b128 v[144:147], v232 offset:26304
	s_waitcnt lgkmcnt(8)
	v_mfma_f32_16x16x32_bf16 v[20:23], v[148:151], v[84:87], 0
	v_mfma_f32_16x16x32_bf16 v[20:23], v[152:155], v[88:91], v[20:23]
	v_mfma_f32_16x16x32_bf16 v[20:23], v[172:175], v[92:95], v[20:23]
	v_mfma_f32_16x16x32_bf16 v[20:23], v[176:179], v[96:99], v[20:23]
	ds_read_b128 v[148:151], v232 offset:30464
	ds_read_b128 v[152:155], v232 offset:30528
	ds_read_b128 v[172:175], v232 offset:30592
	ds_read_b128 v[176:179], v232 offset:30656
	s_waitcnt lgkmcnt(8)
	v_mfma_f32_16x16x32_bf16 v[24:27], v[180:183], v[84:87], 0
	v_mfma_f32_16x16x32_bf16 v[24:27], v[184:187], v[88:91], v[24:27]
	v_mfma_f32_16x16x32_bf16 v[24:27], v[188:191], v[92:95], v[24:27]
	v_mfma_f32_16x16x32_bf16 v[24:27], v[200:203], v[96:99], v[24:27]
	s_waitcnt lgkmcnt(4)
	v_mfma_f32_16x16x32_bf16 v[28:31], v[132:135], v[84:87], 0
	v_mfma_f32_16x16x32_bf16 v[28:31], v[136:139], v[88:91], v[28:31]
	v_mfma_f32_16x16x32_bf16 v[28:31], v[140:143], v[92:95], v[28:31]
	v_mfma_f32_16x16x32_bf16 v[28:31], v[144:147], v[96:99], v[28:31]
	s_waitcnt lgkmcnt(0)
	v_mfma_f32_16x16x32_bf16 v[32:35], v[148:151], v[84:87], 0
	v_mfma_f32_16x16x32_bf16 v[32:35], v[152:155], v[88:91], v[32:35]
	v_mfma_f32_16x16x32_bf16 v[32:35], v[172:175], v[92:95], v[32:35]
	v_mfma_f32_16x16x32_bf16 v[32:35], v[176:179], v[96:99], v[32:35]
	s_branch .Lfix_mmdone_t7

.Lfix_mmdone_t7:
	s_waitcnt vmcnt(16)
	v_lshlrev_b32_e32 v220, 16, v100
	v_and_b32_e32 v221, 0xffff0000, v100
	v_lshlrev_b32_e32 v222, 16, v101
	v_and_b32_e32 v223, 0xffff0000, v101
	v_pk_add_f32 v[4:5], v[4:5], v[220:221]
	v_pk_add_f32 v[6:7], v[6:7], v[222:223]
	v_pk_mul_f32 v[224:225], v[4:5], v[4:5]
	v_pk_fma_f32 v[224:225], v[6:7], v[6:7], v[224:225]
	v_lshlrev_b32_e32 v220, 16, v102
	v_and_b32_e32 v221, 0xffff0000, v102
	v_lshlrev_b32_e32 v222, 16, v103
	v_and_b32_e32 v223, 0xffff0000, v103
	v_pk_add_f32 v[8:9], v[8:9], v[220:221]
	v_pk_add_f32 v[10:11], v[10:11], v[222:223]
	v_pk_fma_f32 v[224:225], v[8:9], v[8:9], v[224:225]
	v_pk_fma_f32 v[224:225], v[10:11], v[10:11], v[224:225]
	v_lshlrev_b32_e32 v220, 16, v104
	v_and_b32_e32 v221, 0xffff0000, v104
	v_lshlrev_b32_e32 v222, 16, v105
	v_and_b32_e32 v223, 0xffff0000, v105
	v_pk_add_f32 v[12:13], v[12:13], v[220:221]
	v_pk_add_f32 v[14:15], v[14:15], v[222:223]
	v_pk_fma_f32 v[224:225], v[12:13], v[12:13], v[224:225]
	v_pk_fma_f32 v[224:225], v[14:15], v[14:15], v[224:225]
	v_lshlrev_b32_e32 v220, 16, v106
	v_and_b32_e32 v221, 0xffff0000, v106
	v_lshlrev_b32_e32 v222, 16, v107
	v_and_b32_e32 v223, 0xffff0000, v107
	v_pk_add_f32 v[16:17], v[16:17], v[220:221]
	v_pk_add_f32 v[18:19], v[18:19], v[222:223]
	v_pk_fma_f32 v[224:225], v[16:17], v[16:17], v[224:225]
	v_pk_fma_f32 v[224:225], v[18:19], v[18:19], v[224:225]
	v_lshlrev_b32_e32 v220, 16, v108
	v_and_b32_e32 v221, 0xffff0000, v108
	v_lshlrev_b32_e32 v222, 16, v109
	v_and_b32_e32 v223, 0xffff0000, v109
	v_pk_add_f32 v[20:21], v[20:21], v[220:221]
	v_pk_add_f32 v[22:23], v[22:23], v[222:223]
	v_pk_fma_f32 v[224:225], v[20:21], v[20:21], v[224:225]
	v_pk_fma_f32 v[224:225], v[22:23], v[22:23], v[224:225]
	v_lshlrev_b32_e32 v220, 16, v110
	v_and_b32_e32 v221, 0xffff0000, v110
	v_lshlrev_b32_e32 v222, 16, v111
	v_and_b32_e32 v223, 0xffff0000, v111
	v_pk_add_f32 v[24:25], v[24:25], v[220:221]
	v_pk_add_f32 v[26:27], v[26:27], v[222:223]
	v_pk_fma_f32 v[224:225], v[24:25], v[24:25], v[224:225]
	v_pk_fma_f32 v[224:225], v[26:27], v[26:27], v[224:225]
	v_lshlrev_b32_e32 v220, 16, v112
	v_and_b32_e32 v221, 0xffff0000, v112
	v_lshlrev_b32_e32 v222, 16, v113
	v_and_b32_e32 v223, 0xffff0000, v113
	v_pk_add_f32 v[28:29], v[28:29], v[220:221]
	v_pk_add_f32 v[30:31], v[30:31], v[222:223]
	v_pk_fma_f32 v[224:225], v[28:29], v[28:29], v[224:225]
	v_pk_fma_f32 v[224:225], v[30:31], v[30:31], v[224:225]
	v_lshlrev_b32_e32 v220, 16, v114
	v_and_b32_e32 v221, 0xffff0000, v114
	v_lshlrev_b32_e32 v222, 16, v115
	v_and_b32_e32 v223, 0xffff0000, v115
	v_pk_add_f32 v[32:33], v[32:33], v[220:221]
	v_pk_add_f32 v[34:35], v[34:35], v[222:223]
	v_pk_fma_f32 v[224:225], v[32:33], v[32:33], v[224:225]
	v_pk_fma_f32 v[224:225], v[34:35], v[34:35], v[224:225]
	v_add_f32_e32 v226, v224, v225
	ds_bpermute_b32 v227, v233, v226
	s_waitcnt lgkmcnt(0)
	v_add_f32_e32 v226, v226, v227
	ds_bpermute_b32 v227, v234, v226
	s_waitcnt lgkmcnt(0)
	v_add_f32_e32 v226, v226, v227
	v_fmamk_f32 v226, v226, 0x3c000000, v195
	v_rsq_f32_e32 v228, v226
	s_nop 0
	s_waitcnt vmcnt(8)
	v_pk_mul_f32 v[4:5], v[4:5], v[228:229] op_sel_hi:[1,0]
	v_pk_mul_f32 v[6:7], v[6:7], v[228:229] op_sel_hi:[1,0]
	v_lshlrev_b32_e32 v220, 16, v116
	v_and_b32_e32 v221, 0xffff0000, v116
	v_lshlrev_b32_e32 v222, 16, v117
	v_and_b32_e32 v223, 0xffff0000, v117
	v_pk_mul_f32 v[4:5], v[4:5], v[220:221]
	v_pk_mul_f32 v[6:7], v[6:7], v[222:223]
	v_cvt_pk_bf16_f32 v116, v4, v5
	v_cvt_pk_bf16_f32 v117, v6, v7
	global_store_dwordx2 v2, v[116:117], s[10:11]
	v_pk_mul_f32 v[8:9], v[8:9], v[228:229] op_sel_hi:[1,0]
	v_pk_mul_f32 v[10:11], v[10:11], v[228:229] op_sel_hi:[1,0]
	v_lshlrev_b32_e32 v220, 16, v118
	v_and_b32_e32 v221, 0xffff0000, v118
	v_lshlrev_b32_e32 v222, 16, v119
	v_and_b32_e32 v223, 0xffff0000, v119
	v_pk_mul_f32 v[8:9], v[8:9], v[220:221]
	v_pk_mul_f32 v[10:11], v[10:11], v[222:223]
	v_cvt_pk_bf16_f32 v118, v8, v9
	v_cvt_pk_bf16_f32 v119, v10, v11
	global_store_dwordx2 v2, v[118:119], s[10:11] offset:32
	v_pk_mul_f32 v[12:13], v[12:13], v[228:229] op_sel_hi:[1,0]
	v_pk_mul_f32 v[14:15], v[14:15], v[228:229] op_sel_hi:[1,0]
	v_lshlrev_b32_e32 v220, 16, v120
	v_and_b32_e32 v221, 0xffff0000, v120
	v_lshlrev_b32_e32 v222, 16, v121
	v_and_b32_e32 v223, 0xffff0000, v121
	v_pk_mul_f32 v[12:13], v[12:13], v[220:221]
	v_pk_mul_f32 v[14:15], v[14:15], v[222:223]
	v_cvt_pk_bf16_f32 v120, v12, v13
	v_cvt_pk_bf16_f32 v121, v14, v15
	global_store_dwordx2 v2, v[120:121], s[10:11] offset:64
	v_pk_mul_f32 v[16:17], v[16:17], v[228:229] op_sel_hi:[1,0]
	v_pk_mul_f32 v[18:19], v[18:19], v[228:229] op_sel_hi:[1,0]
	v_lshlrev_b32_e32 v220, 16, v122
	v_and_b32_e32 v221, 0xffff0000, v122
	v_lshlrev_b32_e32 v222, 16, v123
	v_and_b32_e32 v223, 0xffff0000, v123
	v_pk_mul_f32 v[16:17], v[16:17], v[220:221]
	v_pk_mul_f32 v[18:19], v[18:19], v[222:223]
	v_cvt_pk_bf16_f32 v122, v16, v17
	v_cvt_pk_bf16_f32 v123, v18, v19
	global_store_dwordx2 v2, v[122:123], s[10:11] offset:96
	v_pk_mul_f32 v[20:21], v[20:21], v[228:229] op_sel_hi:[1,0]
	v_pk_mul_f32 v[22:23], v[22:23], v[228:229] op_sel_hi:[1,0]
	v_lshlrev_b32_e32 v220, 16, v124
	v_and_b32_e32 v221, 0xffff0000, v124
	v_lshlrev_b32_e32 v222, 16, v125
	v_and_b32_e32 v223, 0xffff0000, v125
	v_pk_mul_f32 v[20:21], v[20:21], v[220:221]
	v_pk_mul_f32 v[22:23], v[22:23], v[222:223]
	v_cvt_pk_bf16_f32 v124, v20, v21
	v_cvt_pk_bf16_f32 v125, v22, v23
	global_store_dwordx2 v2, v[124:125], s[10:11] offset:128
	v_pk_mul_f32 v[24:25], v[24:25], v[228:229] op_sel_hi:[1,0]
	v_pk_mul_f32 v[26:27], v[26:27], v[228:229] op_sel_hi:[1,0]
	v_lshlrev_b32_e32 v220, 16, v126
	v_and_b32_e32 v221, 0xffff0000, v126
	v_lshlrev_b32_e32 v222, 16, v127
	v_and_b32_e32 v223, 0xffff0000, v127
	v_pk_mul_f32 v[24:25], v[24:25], v[220:221]
	v_pk_mul_f32 v[26:27], v[26:27], v[222:223]
	v_cvt_pk_bf16_f32 v126, v24, v25
	v_cvt_pk_bf16_f32 v127, v26, v27
	global_store_dwordx2 v2, v[126:127], s[10:11] offset:160
	v_pk_mul_f32 v[28:29], v[28:29], v[228:229] op_sel_hi:[1,0]
	v_pk_mul_f32 v[30:31], v[30:31], v[228:229] op_sel_hi:[1,0]
	v_lshlrev_b32_e32 v220, 16, v128
	v_and_b32_e32 v221, 0xffff0000, v128
	v_lshlrev_b32_e32 v222, 16, v129
	v_and_b32_e32 v223, 0xffff0000, v129
	v_pk_mul_f32 v[28:29], v[28:29], v[220:221]
	v_pk_mul_f32 v[30:31], v[30:31], v[222:223]
	v_cvt_pk_bf16_f32 v128, v28, v29
	v_cvt_pk_bf16_f32 v129, v30, v31
	global_store_dwordx2 v2, v[128:129], s[10:11] offset:192
	v_pk_mul_f32 v[32:33], v[32:33], v[228:229] op_sel_hi:[1,0]
	v_pk_mul_f32 v[34:35], v[34:35], v[228:229] op_sel_hi:[1,0]
	v_lshlrev_b32_e32 v220, 16, v130
	v_and_b32_e32 v221, 0xffff0000, v130
	v_lshlrev_b32_e32 v222, 16, v131
	v_and_b32_e32 v223, 0xffff0000, v131
	v_pk_mul_f32 v[32:33], v[32:33], v[220:221]
	v_pk_mul_f32 v[34:35], v[34:35], v[222:223]
	v_cvt_pk_bf16_f32 v130, v32, v33
	v_cvt_pk_bf16_f32 v131, v34, v35
	global_store_dwordx2 v2, v[130:131], s[10:11] offset:224
	s_add_u32 s10, s10, 0x8000
	s_addc_u32 s11, s11, 0
.Lfix_end:
.LBB0_746:
	s_waitcnt lgkmcnt(0)
	s_barrier

	.amdhsa_kernel _Z14fwd_megakernel4Args
		.amdhsa_group_segment_fixed_size 0
		.amdhsa_private_segment_fixed_size 0
		.amdhsa_kernarg_size 416
		.amdhsa_user_sgpr_count 2
		.amdhsa_user_sgpr_dispatch_ptr 0
		.amdhsa_user_sgpr_queue_ptr 0
		.amdhsa_user_sgpr_kernarg_segment_ptr 1
		.amdhsa_user_sgpr_dispatch_id 0
		.amdhsa_user_sgpr_kernarg_preload_length 0
		.amdhsa_user_sgpr_kernarg_preload_offset 0
		.amdhsa_user_sgpr_private_segment_size 0
		.amdhsa_uses_dynamic_stack 0
		.amdhsa_enable_private_segment 0
		.amdhsa_system_sgpr_workgroup_id_x 1
		.amdhsa_system_sgpr_workgroup_id_y 0
		.amdhsa_system_sgpr_workgroup_id_z 0
		.amdhsa_system_sgpr_workgroup_info 0
		.amdhsa_system_vgpr_workitem_id 2
		.amdhsa_next_free_vgpr 247
		.amdhsa_next_free_sgpr 102
		.amdhsa_accum_offset 248
		.amdhsa_reserve_vcc 1
		.amdhsa_float_round_mode_32 0
		.amdhsa_float_round_mode_16_64 0
		.amdhsa_float_denorm_mode_32 3
		.amdhsa_float_denorm_mode_16_64 3
		.amdhsa_dx10_clamp 1
		.amdhsa_ieee_mode 1
		.amdhsa_fp16_overflow 0
		.amdhsa_tg_split 0
		.amdhsa_exception_fp_ieee_invalid_op 0
		.amdhsa_exception_fp_denorm_src 0
		.amdhsa_exception_fp_ieee_div_zero 0
		.amdhsa_exception_fp_ieee_overflow 0
		.amdhsa_exception_fp_ieee_underflow 0
		.amdhsa_exception_fp_ieee_inexact 0
		.amdhsa_exception_int_div_zero 0
	.end_amdhsa_kernel

.Lfunc_end0:
	.size	_Z14fwd_megakernel4Args, .Lfunc_end0-_Z14fwd_megakernel4Args
	.set _Z14fwd_megakernel4Args.num_vgpr, 247
	.set _Z14fwd_megakernel4Args.num_agpr, 0
	.set _Z14fwd_megakernel4Args.numbered_sgpr, 102
	.set _Z14fwd_megakernel4Args.num_named_barrier, 0
	.set _Z14fwd_megakernel4Args.private_seg_size, 0
	.set _Z14fwd_megakernel4Args.uses_vcc, 1
	.set _Z14fwd_megakernel4Args.uses_flat_scratch, 0
	.set _Z14fwd_megakernel4Args.has_dyn_sized_stack, 0
	.set _Z14fwd_megakernel4Args.has_recursion, 0
	.set _Z14fwd_megakernel4Args.has_indirect_call, 0

amdhsa.kernels:
  - .agpr_count:     0
    .args:
      - .offset:         0
        .size:           160
        .value_kind:     by_value
      - .offset:         160
        .size:           4
        .value_kind:     hidden_block_count_x
      - .offset:         164
        .size:           4
        .value_kind:     hidden_block_count_y
      - .offset:         168
        .size:           4
        .value_kind:     hidden_block_count_z
      - .offset:         172
        .size:           2
        .value_kind:     hidden_group_size_x
      - .offset:         174
        .size:           2
        .value_kind:     hidden_group_size_y
      - .offset:         176
        .size:           2
        .value_kind:     hidden_group_size_z
      - .offset:         178
        .size:           2
        .value_kind:     hidden_remainder_x
      - .offset:         180
        .size:           2
        .value_kind:     hidden_remainder_y
      - .offset:         182
        .size:           2
        .value_kind:     hidden_remainder_z
      - .offset:         200
        .size:           8
        .value_kind:     hidden_global_offset_x
      - .offset:         208
        .size:           8
        .value_kind:     hidden_global_offset_y
      - .offset:         216
        .size:           8
        .value_kind:     hidden_global_offset_z
      - .offset:         224
        .size:           2
        .value_kind:     hidden_grid_dims
      - .offset:         248
        .size:           8
        .value_kind:     hidden_multigrid_sync_arg
      - .offset:         280
        .size:           4
        .value_kind:     hidden_dynamic_lds_size
    .group_segment_fixed_size: 0
    .kernarg_segment_align: 8
    .kernarg_segment_size: 416
    .language:       OpenCL C
    .language_version:
      - 2
      - 0
    .max_flat_workgroup_size: 512
    .name:           _Z14fwd_megakernel4Args
    .private_segment_fixed_size: 0
    .sgpr_count:     108
    .sgpr_spill_count: 272
    .symbol:         _Z14fwd_megakernel4Args.kd
    .uniform_work_group_size: 1
    .uses_dynamic_stack: false
    .vgpr_count:     247
    .vgpr_spill_count: 0
    .wavefront_size: 64
